# scans rewritten with hoisted decay loads; attention row-max via 16 max3; in-proj epilogue row stats batched; SSD unit/local loads de-serialised
# speedup vs baseline: 1.0518x; 1.0518x over previous
.LBB0_116:
	s_and_b32 s14, s12, 1
	s_mul_i32 s15, s14, 0x8800
	s_mul_i32 s14, s14, 0x9000
	v_add_u32_e32 v2, s15, v178
	v_add_u32_e32 v0, s14, v179
	s_cmp_gt_u32 s2, s3
	v_add_u32_e32 v6, v2, v180
	s_cbranch_scc1 .LBB0_121
	ds_read_b128 v[2:5], v6
	s_waitcnt lgkmcnt(0)
	v_mfma_f32_32x32x16_bf16 v[96:111], v[2:5], v[112:115], 0
	ds_read_b128 v[2:5], v6 offset:8704
	s_waitcnt lgkmcnt(0)
	v_mfma_f32_32x32x16_bf16 v[80:95], v[2:5], v[112:115], 0
	ds_read_b128 v[2:5], v6 offset:32
	s_waitcnt lgkmcnt(0)
	v_mfma_f32_32x32x16_bf16 v[96:111], v[2:5], v[116:119], v[96:111]
	ds_read_b128 v[2:5], v6 offset:8736
	s_waitcnt lgkmcnt(0)
	v_mfma_f32_32x32x16_bf16 v[80:95], v[2:5], v[116:119], v[80:95]
	ds_read_b128 v[2:5], v6 offset:64
	s_waitcnt vmcnt(1) lgkmcnt(0)
	v_mfma_f32_32x32x16_bf16 v[96:111], v[2:5], v[120:123], v[96:111]
	ds_read_b128 v[2:5], v6 offset:8768
	s_waitcnt lgkmcnt(0)
	v_mfma_f32_32x32x16_bf16 v[80:95], v[2:5], v[120:123], v[80:95]
	ds_read_b128 v[2:5], v6 offset:8800
	s_waitcnt vmcnt(0) lgkmcnt(0)
	v_mfma_f32_32x32x16_bf16 v[80:95], v[2:5], v[124:127], v[80:95]
	ds_read_b128 v[2:5], v6 offset:96
	s_waitcnt lgkmcnt(0)
	v_mfma_f32_32x32x16_bf16 v[96:111], v[2:5], v[124:127], v[96:111]
	s_nop 8
	v_max3_f32 v2, v80, v81, v82
	v_max3_f32 v3, v83, v84, v85
	v_max3_f32 v4, v86, v87, v88
	v_max3_f32 v5, v89, v90, v91
	v_max3_f32 v2, v2, v92, v93
	v_max3_f32 v3, v3, v94, v95
	v_max3_f32 v4, v4, v96, v97
	v_max3_f32 v5, v5, v98, v99
	v_max3_f32 v2, v2, v100, v101
	v_max3_f32 v3, v3, v102, v103
	v_max3_f32 v4, v4, v104, v105
	v_max3_f32 v5, v5, v106, v107
	v_max3_f32 v2, v2, v108, v109
	v_max3_f32 v3, v3, v110, v111
	v_max3_f32 v2, v2, v3, v4
	v_max_f32_e32 v2, v2, v5
	v_and_b32_e32 v4, 64, v220
	v_xor_b32_e32 v3, 32, v220
	v_add_u32_e32 v4, 64, v4
	v_cmp_lt_i32_e32 vcc, v3, v4
	s_nop 1
	v_cndmask_b32_e32 v3, v220, v3, vcc
	v_lshlrev_b32_e32 v3, 2, v3
	ds_bpermute_b32 v3, v3, v2
	s_waitcnt lgkmcnt(0)
	v_max3_f32 v7, v183, v2, v3
	v_cmp_gt_f32_e32 vcc, v7, v183
	s_cbranch_vccz .LBB0_119
	v_sub_f32_e32 v2, v183, v7
	v_mul_f32_e32 v2, 0x3e38aa3b, v2
	v_exp_f32_e32 v2, v2
	s_nop 0
	v_pk_mul_f32 v[78:79], v[78:79], v[2:3] op_sel_hi:[1,0]
	v_pk_mul_f32 v[76:77], v[76:77], v[2:3] op_sel_hi:[1,0]
	v_pk_mul_f32 v[74:75], v[74:75], v[2:3] op_sel_hi:[1,0]
	v_pk_mul_f32 v[72:73], v[72:73], v[2:3] op_sel_hi:[1,0]
	v_pk_mul_f32 v[70:71], v[70:71], v[2:3] op_sel_hi:[1,0]
	v_pk_mul_f32 v[68:69], v[68:69], v[2:3] op_sel_hi:[1,0]
	v_pk_mul_f32 v[66:67], v[66:67], v[2:3] op_sel_hi:[1,0]
	v_pk_mul_f32 v[64:65], v[64:65], v[2:3] op_sel_hi:[1,0]
	v_pk_mul_f32 v[62:63], v[62:63], v[2:3] op_sel_hi:[1,0]
	v_pk_mul_f32 v[60:61], v[60:61], v[2:3] op_sel_hi:[1,0]
	v_pk_mul_f32 v[58:59], v[58:59], v[2:3] op_sel_hi:[1,0]
	v_pk_mul_f32 v[56:57], v[56:57], v[2:3] op_sel_hi:[1,0]
	v_pk_mul_f32 v[54:55], v[54:55], v[2:3] op_sel_hi:[1,0]
	v_pk_mul_f32 v[52:53], v[52:53], v[2:3] op_sel_hi:[1,0]
	v_pk_mul_f32 v[50:51], v[50:51], v[2:3] op_sel_hi:[1,0]
	v_pk_mul_f32 v[48:49], v[48:49], v[2:3] op_sel_hi:[1,0]
	v_pk_mul_f32 v[46:47], v[46:47], v[2:3] op_sel_hi:[1,0]
	v_pk_mul_f32 v[44:45], v[44:45], v[2:3] op_sel_hi:[1,0]
	v_pk_mul_f32 v[42:43], v[42:43], v[2:3] op_sel_hi:[1,0]
	v_pk_mul_f32 v[40:41], v[40:41], v[2:3] op_sel_hi:[1,0]
	v_pk_mul_f32 v[38:39], v[38:39], v[2:3] op_sel_hi:[1,0]
	v_pk_mul_f32 v[36:37], v[36:37], v[2:3] op_sel_hi:[1,0]
	v_pk_mul_f32 v[34:35], v[34:35], v[2:3] op_sel_hi:[1,0]
	v_pk_mul_f32 v[32:33], v[32:33], v[2:3] op_sel_hi:[1,0]
	v_pk_mul_f32 v[30:31], v[30:31], v[2:3] op_sel_hi:[1,0]
	v_pk_mul_f32 v[28:29], v[28:29], v[2:3] op_sel_hi:[1,0]
	v_pk_mul_f32 v[26:27], v[26:27], v[2:3] op_sel_hi:[1,0]
	v_pk_mul_f32 v[24:25], v[24:25], v[2:3] op_sel_hi:[1,0]
	v_pk_mul_f32 v[22:23], v[22:23], v[2:3] op_sel_hi:[1,0]
	v_pk_mul_f32 v[20:21], v[20:21], v[2:3] op_sel_hi:[1,0]
	v_pk_mul_f32 v[18:19], v[18:19], v[2:3] op_sel_hi:[1,0]
	v_pk_mul_f32 v[16:17], v[16:17], v[2:3] op_sel_hi:[1,0]
	v_mul_f32_e32 v182, v182, v2

.LBB0_122:
	ds_read_b128 v[2:5], v6 offset:17408
	s_waitcnt lgkmcnt(0)
	v_mfma_f32_32x32x16_bf16 v[96:111], v[2:5], v[112:115], 0
	ds_read_b128 v[2:5], v6 offset:26112
	s_waitcnt lgkmcnt(0)
	v_mfma_f32_32x32x16_bf16 v[80:95], v[2:5], v[112:115], 0
	ds_read_b128 v[2:5], v6 offset:17440
	s_waitcnt lgkmcnt(0)
	v_mfma_f32_32x32x16_bf16 v[96:111], v[2:5], v[116:119], v[96:111]
	ds_read_b128 v[2:5], v6 offset:26144
	s_waitcnt lgkmcnt(0)
	v_mfma_f32_32x32x16_bf16 v[80:95], v[2:5], v[116:119], v[80:95]
	ds_read_b128 v[2:5], v6 offset:17472
	s_waitcnt vmcnt(1) lgkmcnt(0)
	v_mfma_f32_32x32x16_bf16 v[96:111], v[2:5], v[120:123], v[96:111]
	ds_read_b128 v[2:5], v6 offset:26176
	s_waitcnt lgkmcnt(0)
	v_mfma_f32_32x32x16_bf16 v[80:95], v[2:5], v[120:123], v[80:95]
	ds_read_b128 v[2:5], v6 offset:26208
	s_waitcnt vmcnt(0) lgkmcnt(0)
	v_mfma_f32_32x32x16_bf16 v[80:95], v[2:5], v[124:127], v[80:95]
	ds_read_b128 v[2:5], v6 offset:17504
	s_waitcnt lgkmcnt(0)
	v_mfma_f32_32x32x16_bf16 v[96:111], v[2:5], v[124:127], v[96:111]
	s_nop 8
	v_max3_f32 v2, v80, v81, v82
	v_max3_f32 v3, v83, v84, v85
	v_max3_f32 v4, v86, v87, v88
	v_max3_f32 v5, v89, v90, v91
	v_max3_f32 v2, v2, v92, v93
	v_max3_f32 v3, v3, v94, v95
	v_max3_f32 v4, v4, v96, v97
	v_max3_f32 v5, v5, v98, v99
	v_max3_f32 v2, v2, v100, v101
	v_max3_f32 v3, v3, v102, v103
	v_max3_f32 v4, v4, v104, v105
	v_max3_f32 v5, v5, v106, v107
	v_max3_f32 v2, v2, v108, v109
	v_max3_f32 v3, v3, v110, v111
	v_max3_f32 v2, v2, v3, v4
	v_max_f32_e32 v2, v2, v5
	v_and_b32_e32 v4, 64, v220
	v_xor_b32_e32 v3, 32, v220
	v_add_u32_e32 v4, 64, v4
	v_cmp_lt_i32_e32 vcc, v3, v4
	s_nop 1
	v_cndmask_b32_e32 v3, v220, v3, vcc
	v_lshlrev_b32_e32 v3, 2, v3
	ds_bpermute_b32 v3, v3, v2
	s_waitcnt lgkmcnt(0)
	v_max3_f32 v183, v7, v2, v3
	v_cmp_gt_f32_e32 vcc, v183, v7
	s_cbranch_vccz .LBB0_124
	v_sub_f32_e32 v2, v7, v183
	v_mul_f32_e32 v2, 0x3e38aa3b, v2
	v_exp_f32_e32 v2, v2
	s_nop 0
	v_pk_mul_f32 v[78:79], v[78:79], v[2:3] op_sel_hi:[1,0]
	v_pk_mul_f32 v[76:77], v[76:77], v[2:3] op_sel_hi:[1,0]
	v_pk_mul_f32 v[74:75], v[74:75], v[2:3] op_sel_hi:[1,0]
	v_pk_mul_f32 v[72:73], v[72:73], v[2:3] op_sel_hi:[1,0]
	v_pk_mul_f32 v[70:71], v[70:71], v[2:3] op_sel_hi:[1,0]
	v_pk_mul_f32 v[68:69], v[68:69], v[2:3] op_sel_hi:[1,0]
	v_pk_mul_f32 v[66:67], v[66:67], v[2:3] op_sel_hi:[1,0]
	v_pk_mul_f32 v[64:65], v[64:65], v[2:3] op_sel_hi:[1,0]
	v_pk_mul_f32 v[62:63], v[62:63], v[2:3] op_sel_hi:[1,0]
	v_pk_mul_f32 v[60:61], v[60:61], v[2:3] op_sel_hi:[1,0]
	v_pk_mul_f32 v[58:59], v[58:59], v[2:3] op_sel_hi:[1,0]
	v_pk_mul_f32 v[56:57], v[56:57], v[2:3] op_sel_hi:[1,0]
	v_pk_mul_f32 v[54:55], v[54:55], v[2:3] op_sel_hi:[1,0]
	v_pk_mul_f32 v[52:53], v[52:53], v[2:3] op_sel_hi:[1,0]
	v_pk_mul_f32 v[50:51], v[50:51], v[2:3] op_sel_hi:[1,0]
	v_pk_mul_f32 v[48:49], v[48:49], v[2:3] op_sel_hi:[1,0]
	v_pk_mul_f32 v[46:47], v[46:47], v[2:3] op_sel_hi:[1,0]
	v_pk_mul_f32 v[44:45], v[44:45], v[2:3] op_sel_hi:[1,0]
	v_pk_mul_f32 v[42:43], v[42:43], v[2:3] op_sel_hi:[1,0]
	v_pk_mul_f32 v[40:41], v[40:41], v[2:3] op_sel_hi:[1,0]
	v_pk_mul_f32 v[38:39], v[38:39], v[2:3] op_sel_hi:[1,0]
	v_pk_mul_f32 v[36:37], v[36:37], v[2:3] op_sel_hi:[1,0]
	v_pk_mul_f32 v[34:35], v[34:35], v[2:3] op_sel_hi:[1,0]
	v_pk_mul_f32 v[32:33], v[32:33], v[2:3] op_sel_hi:[1,0]
	v_pk_mul_f32 v[30:31], v[30:31], v[2:3] op_sel_hi:[1,0]
	v_pk_mul_f32 v[28:29], v[28:29], v[2:3] op_sel_hi:[1,0]
	v_pk_mul_f32 v[26:27], v[26:27], v[2:3] op_sel_hi:[1,0]
	v_pk_mul_f32 v[24:25], v[24:25], v[2:3] op_sel_hi:[1,0]
	v_pk_mul_f32 v[22:23], v[22:23], v[2:3] op_sel_hi:[1,0]
	v_pk_mul_f32 v[20:21], v[20:21], v[2:3] op_sel_hi:[1,0]
	v_pk_mul_f32 v[18:19], v[18:19], v[2:3] op_sel_hi:[1,0]
	v_pk_mul_f32 v[16:17], v[16:17], v[2:3] op_sel_hi:[1,0]
	v_mul_f32_e32 v182, v182, v2

.LBB0_177:
	v_lshl_add_u32 v174, s2, 8, v159
	v_ashrrev_i32_e32 v175, 31, v174
	v_lshl_add_u64 v[130:131], v[174:175], 2, s[8:9]
	global_load_dword v172, v[130:131], off
	global_load_dword v178, v[130:131], off offset:64
	global_load_dword v182, v[130:131], off offset:128
	global_load_dword v186, v[130:131], off offset:192
	global_load_dword v190, v[130:131], off offset:512
	global_load_dword v194, v[130:131], off offset:576
	global_load_dword v198, v[130:131], off offset:640
	global_load_dword v200, v[130:131], off offset:704
	s_mov_b32 s2, 0x800000
	v_or_b32_e32 v170, 16, v174
	v_or_b32_e32 v176, 32, v174
	v_or_b32_e32 v180, 48, v174
	v_add_u32_e32 v184, 0x80, v174
	v_add_u32_e32 v188, 0x90, v174
	v_add_u32_e32 v192, 0xa0, v174
	v_add_u32_e32 v196, 0xb0, v174
	v_ashrrev_i32_e32 v171, 31, v170
	v_ashrrev_i32_e32 v177, 31, v176
	v_ashrrev_i32_e32 v181, 31, v180
	v_ashrrev_i32_e32 v185, 31, v184
	v_ashrrev_i32_e32 v189, 31, v188
	v_ashrrev_i32_e32 v193, 31, v192
	v_ashrrev_i32_e32 v197, 31, v196
	s_cmp_lg_u32 s49, s37
	s_waitcnt vmcnt(0)
	v_fmamk_f32 v172, v172, 0x3a800000, v219
	v_cmp_gt_f32_e32 vcc, s2, v172
	v_mul_f32_e32 v132, 0x4b800000, v172
	s_nop 0
	v_cndmask_b32_e32 v172, v172, v132, vcc
	v_rsq_f32_e32 v172, v172
	s_nop 0
	v_mul_f32_e32 v132, 0x45800000, v172
	v_cndmask_b32_e32 v172, v172, v132, vcc
	v_fmamk_f32 v178, v178, 0x3a800000, v219
	v_cmp_gt_f32_e32 vcc, s2, v178
	v_mul_f32_e32 v132, 0x4b800000, v178
	s_nop 0
	v_cndmask_b32_e32 v178, v178, v132, vcc
	v_rsq_f32_e32 v178, v178
	s_nop 0
	v_mul_f32_e32 v132, 0x45800000, v178
	v_cndmask_b32_e32 v178, v178, v132, vcc
	v_fmamk_f32 v182, v182, 0x3a800000, v219
	v_cmp_gt_f32_e32 vcc, s2, v182
	v_mul_f32_e32 v132, 0x4b800000, v182
	s_nop 0
	v_cndmask_b32_e32 v182, v182, v132, vcc
	v_rsq_f32_e32 v182, v182
	s_nop 0
	v_mul_f32_e32 v132, 0x45800000, v182
	v_cndmask_b32_e32 v182, v182, v132, vcc
	v_fmamk_f32 v186, v186, 0x3a800000, v219
	v_cmp_gt_f32_e32 vcc, s2, v186
	v_mul_f32_e32 v132, 0x4b800000, v186
	s_nop 0
	v_cndmask_b32_e32 v186, v186, v132, vcc
	v_rsq_f32_e32 v186, v186
	s_nop 0
	v_mul_f32_e32 v132, 0x45800000, v186
	v_cndmask_b32_e32 v186, v186, v132, vcc
	v_fmamk_f32 v190, v190, 0x3a800000, v219
	v_cmp_gt_f32_e32 vcc, s2, v190
	v_mul_f32_e32 v132, 0x4b800000, v190
	s_nop 0
	v_cndmask_b32_e32 v190, v190, v132, vcc
	v_rsq_f32_e32 v190, v190
	s_nop 0
	v_mul_f32_e32 v132, 0x45800000, v190
	v_cndmask_b32_e32 v190, v190, v132, vcc
	v_fmamk_f32 v194, v194, 0x3a800000, v219
	v_cmp_gt_f32_e32 vcc, s2, v194
	v_mul_f32_e32 v132, 0x4b800000, v194
	s_nop 0
	v_cndmask_b32_e32 v194, v194, v132, vcc
	v_rsq_f32_e32 v194, v194
	s_nop 0
	v_mul_f32_e32 v132, 0x45800000, v194
	v_cndmask_b32_e32 v194, v194, v132, vcc
	v_fmamk_f32 v198, v198, 0x3a800000, v219
	v_cmp_gt_f32_e32 vcc, s2, v198
	v_mul_f32_e32 v132, 0x4b800000, v198
	s_nop 0
	v_cndmask_b32_e32 v198, v198, v132, vcc
	v_rsq_f32_e32 v198, v198
	s_nop 0
	v_mul_f32_e32 v132, 0x45800000, v198
	v_cndmask_b32_e32 v198, v198, v132, vcc
	v_fmamk_f32 v200, v200, 0x3a800000, v219
	v_cmp_gt_f32_e32 vcc, s2, v200
	v_mul_f32_e32 v132, 0x4b800000, v200
	s_nop 0
	v_cndmask_b32_e32 v200, v200, v132, vcc
	v_rsq_f32_e32 v200, v200
	s_nop 0
	v_mul_f32_e32 v132, 0x45800000, v200
	v_cndmask_b32_e32 v200, v200, v132, vcc
	s_mov_b64 s[2:3], -1
	s_cbranch_scc0 .LBB0_182
	s_lshl_b32 s2, s49, 8
	s_and_b32 s4, s2, 0x300
	s_ashr_i32 s2, s49, 2
	s_ashr_i32 s3, s2, 31
	s_lshl_b64 s[22:23], s[2:3], 25
	v_readlane_b32 s24, v254, 34
	v_readlane_b32 s25, v254, 35
	s_add_u32 s5, s24, s22
	s_addc_u32 s15, s25, s23
	s_cmp_eq_u32 s2, s39
	s_cselect_b32 s17, s44, 0
	s_cselect_b32 s3, s45, 0
	s_cmp_eq_u32 s2, s38
	s_cselect_b32 s3, s43, s3
	s_cselect_b32 s2, s42, s17
	s_cmp_eq_u64 s[2:3], 0
	v_lshlrev_b64 v[212:213], 11, v[174:175]
	v_lshlrev_b64 v[210:211], 11, v[170:171]
	v_lshlrev_b64 v[208:209], 11, v[176:177]
	v_lshlrev_b64 v[206:207], 11, v[180:181]
	v_lshlrev_b32_e32 v0, 1, v158
	v_lshlrev_b64 v[204:205], 11, v[184:185]
	v_lshlrev_b64 v[202:203], 11, v[188:189]
	s_cbranch_scc1 .LBB0_188
	s_lshl_b32 s17, s4, 2
	s_add_u32 s2, s2, s17
	s_addc_u32 s3, s3, 0
	v_lshlrev_b32_e32 v134, 2, v158
	global_load_dwordx4 v[138:141], v134, s[2:3] offset:16
	global_load_dwordx4 v[142:145], v134, s[2:3]
	global_load_dwordx4 v[130:133], v134, s[2:3] offset:528
	s_nop 0
	global_load_dwordx4 v[134:137], v134, s[2:3] offset:512
	s_lshl_b32 s2, s4, 1
	s_add_u32 s2, s5, s2
	s_addc_u32 s3, s15, 0
	v_lshl_add_u64 v[148:149], s[2:3], 0, v[212:213]
	s_waitcnt vmcnt(3)
	v_pk_fma_f32 v[226:227], v[76:77], v[172:173], v[140:141] op_sel_hi:[1,0,1]
	s_waitcnt vmcnt(2)
	v_pk_fma_f32 v[146:147], v[78:79], v[172:173], v[142:143] op_sel_hi:[1,0,1]
	v_pk_fma_f32 v[214:215], v[80:81], v[172:173], v[144:145] op_sel_hi:[1,0,1]
	v_mul_f32_e32 v146, 0xbfb8aa3b, v146
	v_mul_f32_e32 v147, 0xbfb8aa3b, v147
	v_exp_f32_e32 v146, v146
	v_exp_f32_e32 v147, v147
	v_mul_f32_e32 v183, 0xbfb8aa3b, v215
	v_exp_f32_e32 v183, v183
	v_add_f32_e32 v146, 1.0, v146
	v_add_f32_e32 v147, 1.0, v147
	v_rcp_f32_e32 v146, v146
	v_rcp_f32_e32 v147, v147
	v_add_f32_e32 v183, 1.0, v183
	v_rcp_f32_e32 v183, v183
	v_cvt_pk_bf16_f32 v146, v146, v147
	v_mul_f32_e32 v147, 0xbfb8aa3b, v214
	v_lshl_add_u64 v[214:215], v[148:149], 0, v[0:1]
	v_pk_fma_f32 v[148:149], v[74:75], v[172:173], v[138:139] op_sel_hi:[1,0,1]
	v_exp_f32_e32 v147, v147
	v_mul_f32_e32 v148, 0xbfb8aa3b, v148
	v_mul_f32_e32 v149, 0xbfb8aa3b, v149
	v_exp_f32_e32 v148, v148
	v_exp_f32_e32 v149, v149
	v_add_f32_e32 v147, 1.0, v147
	v_rcp_f32_e32 v147, v147
	v_add_f32_e32 v148, 1.0, v148
	v_add_f32_e32 v149, 1.0, v149
	v_rcp_f32_e32 v148, v148
	v_rcp_f32_e32 v149, v149
	v_cvt_pk_bf16_f32 v147, v147, v183
	v_mul_f32_e32 v183, 0xbfb8aa3b, v227
	v_exp_f32_e32 v183, v183
	v_cvt_pk_bf16_f32 v148, v148, v149
	v_mul_f32_e32 v149, 0xbfb8aa3b, v226
	v_exp_f32_e32 v149, v149
	v_add_f32_e32 v183, 1.0, v183
	v_rcp_f32_e32 v183, v183
	s_waitcnt vmcnt(1)
	v_pk_fma_f32 v[226:227], v[124:125], v[172:173], v[132:133] op_sel_hi:[1,0,1]
	v_add_f32_e32 v149, 1.0, v149
	v_rcp_f32_e32 v149, v149
	s_nop 0
	v_cvt_pk_bf16_f32 v149, v149, v183
	global_store_dwordx4 v[214:215], v[146:149], off
	v_mul_f32_e32 v183, 0xbfb8aa3b, v227
	v_exp_f32_e32 v183, v183
	s_waitcnt vmcnt(1)
	v_pk_fma_f32 v[146:147], v[126:127], v[172:173], v[134:135] op_sel_hi:[1,0,1]
	v_pk_fma_f32 v[148:149], v[128:129], v[172:173], v[136:137] op_sel_hi:[1,0,1]
	v_mul_f32_e32 v146, 0xbfb8aa3b, v146
	v_mul_f32_e32 v147, 0xbfb8aa3b, v147
	v_exp_f32_e32 v146, v146
	v_exp_f32_e32 v147, v147
	v_add_f32_e32 v183, 1.0, v183
	v_rcp_f32_e32 v183, v183
	v_add_f32_e32 v146, 1.0, v146
	v_add_f32_e32 v147, 1.0, v147
	v_rcp_f32_e32 v146, v146
	v_rcp_f32_e32 v147, v147
	s_nop 0
	v_cvt_pk_bf16_f32 v146, v146, v147
	v_mul_f32_e32 v147, 0xbfb8aa3b, v148
	v_mul_f32_e32 v148, 0xbfb8aa3b, v149
	v_exp_f32_e32 v147, v147
	v_exp_f32_e32 v148, v148
	v_add_f32_e32 v147, 1.0, v147
	v_add_f32_e32 v148, 1.0, v148
	v_rcp_f32_e32 v147, v147
	v_rcp_f32_e32 v148, v148
	s_nop 0
	v_cvt_pk_bf16_f32 v147, v147, v148
	v_pk_fma_f32 v[148:149], v[122:123], v[172:173], v[130:131] op_sel_hi:[1,0,1]
	s_nop 0
	v_mul_f32_e32 v148, 0xbfb8aa3b, v148
	v_mul_f32_e32 v149, 0xbfb8aa3b, v149
	v_exp_f32_e32 v148, v148
	v_exp_f32_e32 v149, v149
	v_add_f32_e32 v148, 1.0, v148
	v_add_f32_e32 v149, 1.0, v149
	v_rcp_f32_e32 v148, v148
	v_rcp_f32_e32 v149, v149
	s_nop 0
	v_cvt_pk_bf16_f32 v148, v148, v149
	v_mul_f32_e32 v149, 0xbfb8aa3b, v226
	v_exp_f32_e32 v149, v149
	s_nop 0
	v_add_f32_e32 v149, 1.0, v149
	v_rcp_f32_e32 v149, v149
	s_nop 0
	v_cvt_pk_bf16_f32 v149, v149, v183
	global_store_dwordx4 v[214:215], v[146:149], off offset:256
	v_pk_fma_f32 v[214:215], v[70:71], v[178:179], v[142:143] op_sel_hi:[1,0,1]
	s_nop 0
	v_pk_fma_f32 v[148:149], v[72:73], v[178:179], v[144:145] op_sel_hi:[1,0,1]
	v_mul_f32_e32 v183, 0xbfb8aa3b, v214
	v_mul_f32_e32 v148, 0xbfb8aa3b, v148
	v_mul_f32_e32 v149, 0xbfb8aa3b, v149
	v_exp_f32_e32 v148, v148
	v_exp_f32_e32 v149, v149
	v_mul_f32_e32 v187, 0xbfb8aa3b, v215
	v_exp_f32_e32 v183, v183
	v_exp_f32_e32 v187, v187
	v_add_f32_e32 v148, 1.0, v148
	v_add_f32_e32 v149, 1.0, v149
	v_rcp_f32_e32 v148, v148
	v_rcp_f32_e32 v149, v149
	v_add_f32_e32 v183, 1.0, v183
	v_add_f32_e32 v187, 1.0, v187
	v_rcp_f32_e32 v183, v183
	v_rcp_f32_e32 v187, v187
	v_cvt_pk_bf16_f32 v243, v148, v149
	v_pk_fma_f32 v[148:149], v[64:65], v[178:179], v[140:141] op_sel_hi:[1,0,1]
	v_pk_fma_f32 v[214:215], v[62:63], v[178:179], v[138:139] op_sel_hi:[1,0,1]
	v_mul_f32_e32 v148, 0xbfb8aa3b, v148
	v_mul_f32_e32 v149, 0xbfb8aa3b, v149
	v_exp_f32_e32 v148, v148
	v_exp_f32_e32 v149, v149
	v_cvt_pk_bf16_f32 v242, v183, v187
	v_mul_f32_e32 v183, 0xbfb8aa3b, v214
	v_mul_f32_e32 v187, 0xbfb8aa3b, v215
	v_exp_f32_e32 v183, v183
	v_exp_f32_e32 v187, v187
	v_add_f32_e32 v148, 1.0, v148
	v_add_f32_e32 v149, 1.0, v149
	v_rcp_f32_e32 v148, v148
	v_rcp_f32_e32 v149, v149
	v_add_f32_e32 v183, 1.0, v183
	v_add_f32_e32 v187, 1.0, v187
	v_rcp_f32_e32 v183, v183
	v_rcp_f32_e32 v187, v187
	v_cvt_pk_bf16_f32 v245, v148, v149
	v_pk_fma_f32 v[148:149], v[120:121], v[178:179], v[136:137] op_sel_hi:[1,0,1]
	v_pk_fma_f32 v[214:215], v[118:119], v[178:179], v[134:135] op_sel_hi:[1,0,1]
	v_mul_f32_e32 v148, 0xbfb8aa3b, v148
	v_mul_f32_e32 v149, 0xbfb8aa3b, v149
	v_cvt_pk_bf16_f32 v244, v183, v187
	v_mul_f32_e32 v183, 0xbfb8aa3b, v214
	v_mul_f32_e32 v187, 0xbfb8aa3b, v215
	v_exp_f32_e32 v148, v148
	v_exp_f32_e32 v149, v149
	v_exp_f32_e32 v183, v183
	v_exp_f32_e32 v187, v187
	v_add_f32_e32 v148, 1.0, v148
	v_add_f32_e32 v149, 1.0, v149
	v_add_f32_e32 v183, 1.0, v183
	v_add_f32_e32 v187, 1.0, v187
	v_rcp_f32_e32 v148, v148
	v_rcp_f32_e32 v149, v149
	v_rcp_f32_e32 v183, v183
	v_rcp_f32_e32 v187, v187
	v_lshl_add_u64 v[146:147], s[2:3], 0, v[210:211]
	v_lshl_add_u64 v[146:147], v[146:147], 0, v[0:1]
	global_store_dwordx4 v[146:147], v[242:245], off
	v_pk_fma_f32 v[214:215], v[114:115], v[178:179], v[130:131] op_sel_hi:[1,0,1]
	s_nop 0
	v_cvt_pk_bf16_f32 v243, v148, v149
	v_pk_fma_f32 v[148:149], v[116:117], v[178:179], v[132:133] op_sel_hi:[1,0,1]
	v_cvt_pk_bf16_f32 v242, v183, v187
	v_mul_f32_e32 v183, 0xbfb8aa3b, v214
	v_mul_f32_e32 v148, 0xbfb8aa3b, v148
	v_mul_f32_e32 v149, 0xbfb8aa3b, v149
	v_exp_f32_e32 v183, v183
	v_mul_f32_e32 v187, 0xbfb8aa3b, v215
	v_exp_f32_e32 v148, v148
	v_exp_f32_e32 v149, v149
	v_exp_f32_e32 v187, v187
	v_add_f32_e32 v183, 1.0, v183
	v_add_f32_e32 v148, 1.0, v148
	v_add_f32_e32 v149, 1.0, v149
	v_rcp_f32_e32 v183, v183
	v_add_f32_e32 v187, 1.0, v187
	v_rcp_f32_e32 v148, v148
	v_rcp_f32_e32 v149, v149
	v_rcp_f32_e32 v187, v187
	v_pk_fma_f32 v[214:215], v[54:55], v[182:183], v[142:143] op_sel_hi:[1,0,1]
	v_cvt_pk_bf16_f32 v245, v148, v149
	v_pk_fma_f32 v[148:149], v[56:57], v[182:183], v[144:145] op_sel_hi:[1,0,1]
	v_cvt_pk_bf16_f32 v244, v183, v187
	v_mul_f32_e32 v183, 0xbfb8aa3b, v214
	v_mul_f32_e32 v148, 0xbfb8aa3b, v148
	v_mul_f32_e32 v149, 0xbfb8aa3b, v149
	v_exp_f32_e32 v183, v183
	v_mul_f32_e32 v187, 0xbfb8aa3b, v215
	v_exp_f32_e32 v148, v148
	v_exp_f32_e32 v149, v149
	v_exp_f32_e32 v187, v187
	v_add_f32_e32 v183, 1.0, v183
	v_add_f32_e32 v148, 1.0, v148
	v_add_f32_e32 v149, 1.0, v149
	v_rcp_f32_e32 v183, v183
	v_add_f32_e32 v187, 1.0, v187
	v_rcp_f32_e32 v148, v148
	v_rcp_f32_e32 v149, v149
	v_rcp_f32_e32 v187, v187
	global_store_dwordx4 v[146:147], v[242:245], off offset:256
	v_pk_fma_f32 v[214:215], v[50:51], v[182:183], v[138:139] op_sel_hi:[1,0,1]
	v_lshl_add_u64 v[146:147], s[2:3], 0, v[208:209]
	v_cvt_pk_bf16_f32 v243, v148, v149
	v_pk_fma_f32 v[148:149], v[52:53], v[182:183], v[140:141] op_sel_hi:[1,0,1]
	v_cvt_pk_bf16_f32 v242, v183, v187
	v_mul_f32_e32 v183, 0xbfb8aa3b, v214
	v_mul_f32_e32 v148, 0xbfb8aa3b, v148
	v_mul_f32_e32 v149, 0xbfb8aa3b, v149
	v_exp_f32_e32 v183, v183
	v_mul_f32_e32 v187, 0xbfb8aa3b, v215
	v_exp_f32_e32 v148, v148
	v_exp_f32_e32 v149, v149
	v_exp_f32_e32 v187, v187
	v_add_f32_e32 v183, 1.0, v183
	v_add_f32_e32 v148, 1.0, v148
	v_add_f32_e32 v149, 1.0, v149
	v_rcp_f32_e32 v183, v183
	v_add_f32_e32 v187, 1.0, v187
	v_rcp_f32_e32 v148, v148
	v_rcp_f32_e32 v149, v149
	v_rcp_f32_e32 v187, v187
	v_pk_fma_f32 v[214:215], v[110:111], v[182:183], v[134:135] op_sel_hi:[1,0,1]
	v_lshl_add_u64 v[146:147], v[146:147], 0, v[0:1]
	v_cvt_pk_bf16_f32 v245, v148, v149
	v_pk_fma_f32 v[148:149], v[112:113], v[182:183], v[136:137] op_sel_hi:[1,0,1]
	v_cvt_pk_bf16_f32 v244, v183, v187
	v_mul_f32_e32 v183, 0xbfb8aa3b, v214
	v_mul_f32_e32 v148, 0xbfb8aa3b, v148
	v_mul_f32_e32 v149, 0xbfb8aa3b, v149
	v_exp_f32_e32 v183, v183
	v_mul_f32_e32 v187, 0xbfb8aa3b, v215
	v_exp_f32_e32 v148, v148
	v_exp_f32_e32 v149, v149
	v_exp_f32_e32 v187, v187
	v_add_f32_e32 v183, 1.0, v183
	v_add_f32_e32 v148, 1.0, v148
	v_add_f32_e32 v149, 1.0, v149
	v_rcp_f32_e32 v183, v183
	v_add_f32_e32 v187, 1.0, v187
	v_rcp_f32_e32 v148, v148
	v_rcp_f32_e32 v149, v149
	v_rcp_f32_e32 v187, v187
	global_store_dwordx4 v[146:147], v[242:245], off
	v_pk_fma_f32 v[214:215], v[106:107], v[182:183], v[130:131] op_sel_hi:[1,0,1]
	s_nop 0
	v_cvt_pk_bf16_f32 v243, v148, v149
	v_pk_fma_f32 v[148:149], v[108:109], v[182:183], v[132:133] op_sel_hi:[1,0,1]
	v_cvt_pk_bf16_f32 v242, v183, v187
	v_mul_f32_e32 v187, 0xbfb8aa3b, v215
	v_mul_f32_e32 v148, 0xbfb8aa3b, v148
	v_mul_f32_e32 v149, 0xbfb8aa3b, v149
	v_mul_f32_e32 v183, 0xbfb8aa3b, v214
	v_exp_f32_e32 v187, v187
	v_exp_f32_e32 v148, v148
	v_exp_f32_e32 v149, v149
	v_exp_f32_e32 v183, v183
	v_add_f32_e32 v187, 1.0, v187
	v_add_f32_e32 v148, 1.0, v148
	v_add_f32_e32 v149, 1.0, v149
	v_add_f32_e32 v183, 1.0, v183
	v_rcp_f32_e32 v187, v187
	v_rcp_f32_e32 v148, v148
	v_rcp_f32_e32 v149, v149
	v_rcp_f32_e32 v183, v183
	v_pk_fma_f32 v[214:215], v[42:43], v[186:187], v[142:143] op_sel_hi:[1,0,1]
	v_cvt_pk_bf16_f32 v245, v148, v149
	v_pk_fma_f32 v[148:149], v[44:45], v[186:187], v[144:145] op_sel_hi:[1,0,1]
	v_cvt_pk_bf16_f32 v244, v183, v187
	v_mul_f32_e32 v187, 0xbfb8aa3b, v215
	v_mul_f32_e32 v148, 0xbfb8aa3b, v148
	v_mul_f32_e32 v149, 0xbfb8aa3b, v149
	v_mul_f32_e32 v183, 0xbfb8aa3b, v214
	v_exp_f32_e32 v187, v187
	v_exp_f32_e32 v148, v148
	v_exp_f32_e32 v149, v149
	v_exp_f32_e32 v183, v183
	v_add_f32_e32 v187, 1.0, v187
	v_add_f32_e32 v148, 1.0, v148
	v_add_f32_e32 v149, 1.0, v149
	v_add_f32_e32 v183, 1.0, v183
	v_rcp_f32_e32 v187, v187
	v_rcp_f32_e32 v148, v148
	v_rcp_f32_e32 v149, v149
	v_rcp_f32_e32 v183, v183
	global_store_dwordx4 v[146:147], v[242:245], off offset:256
	v_pk_fma_f32 v[214:215], v[34:35], v[186:187], v[138:139] op_sel_hi:[1,0,1]
	v_lshl_add_u64 v[146:147], s[2:3], 0, v[206:207]
	v_cvt_pk_bf16_f32 v243, v148, v149
	v_pk_fma_f32 v[148:149], v[36:37], v[186:187], v[140:141] op_sel_hi:[1,0,1]
	v_cvt_pk_bf16_f32 v242, v183, v187
	v_mul_f32_e32 v187, 0xbfb8aa3b, v215
	v_mul_f32_e32 v148, 0xbfb8aa3b, v148
	v_mul_f32_e32 v149, 0xbfb8aa3b, v149
	v_mul_f32_e32 v183, 0xbfb8aa3b, v214
	v_exp_f32_e32 v187, v187
	v_exp_f32_e32 v148, v148
	v_exp_f32_e32 v149, v149
	v_exp_f32_e32 v183, v183
	v_add_f32_e32 v187, 1.0, v187
	v_add_f32_e32 v148, 1.0, v148
	v_add_f32_e32 v149, 1.0, v149
	v_add_f32_e32 v183, 1.0, v183
	v_rcp_f32_e32 v187, v187
	v_rcp_f32_e32 v148, v148
	v_rcp_f32_e32 v149, v149
	v_rcp_f32_e32 v183, v183
	v_pk_fma_f32 v[214:215], v[102:103], v[186:187], v[134:135] op_sel_hi:[1,0,1]
	v_lshl_add_u64 v[146:147], v[146:147], 0, v[0:1]
	v_cvt_pk_bf16_f32 v245, v148, v149
	v_pk_fma_f32 v[148:149], v[104:105], v[186:187], v[136:137] op_sel_hi:[1,0,1]
	v_cvt_pk_bf16_f32 v244, v183, v187
	v_mul_f32_e32 v187, 0xbfb8aa3b, v215
	v_mul_f32_e32 v148, 0xbfb8aa3b, v148
	v_mul_f32_e32 v149, 0xbfb8aa3b, v149
	v_exp_f32_e32 v187, v187
	v_exp_f32_e32 v148, v148
	v_exp_f32_e32 v149, v149
	global_store_dwordx4 v[146:147], v[242:245], off
	v_add_f32_e32 v187, 1.0, v187
	v_add_f32_e32 v148, 1.0, v148
	v_add_f32_e32 v149, 1.0, v149
	v_rcp_f32_e32 v187, v187
	v_rcp_f32_e32 v148, v148
	v_rcp_f32_e32 v149, v149
	v_mul_f32_e32 v183, 0xbfb8aa3b, v214
	v_exp_f32_e32 v183, v183
	v_pk_fma_f32 v[214:215], v[98:99], v[186:187], v[130:131] op_sel_hi:[1,0,1]
	v_cvt_pk_bf16_f32 v243, v148, v149
	v_pk_fma_f32 v[148:149], v[100:101], v[186:187], v[132:133] op_sel_hi:[1,0,1]
	v_add_f32_e32 v183, 1.0, v183
	v_mul_f32_e32 v148, 0xbfb8aa3b, v148
	v_mul_f32_e32 v149, 0xbfb8aa3b, v149
	v_exp_f32_e32 v148, v148
	v_exp_f32_e32 v149, v149
	v_rcp_f32_e32 v183, v183
	v_add_f32_e32 v148, 1.0, v148
	v_add_f32_e32 v149, 1.0, v149
	v_rcp_f32_e32 v148, v148
	v_rcp_f32_e32 v149, v149
	v_cvt_pk_bf16_f32 v242, v183, v187
	v_mul_f32_e32 v183, 0xbfb8aa3b, v214
	v_mul_f32_e32 v187, 0xbfb8aa3b, v215
	v_cvt_pk_bf16_f32 v245, v148, v149
	v_pk_fma_f32 v[148:149], v[32:33], v[190:191], v[144:145] op_sel_hi:[1,0,1]
	v_exp_f32_e32 v183, v183
	v_exp_f32_e32 v187, v187
	v_mul_f32_e32 v148, 0xbfb8aa3b, v148
	v_mul_f32_e32 v149, 0xbfb8aa3b, v149
	v_exp_f32_e32 v148, v148
	v_exp_f32_e32 v149, v149
	v_add_f32_e32 v183, 1.0, v183
	v_add_f32_e32 v187, 1.0, v187
	v_rcp_f32_e32 v183, v183
	v_rcp_f32_e32 v187, v187
	v_add_f32_e32 v148, 1.0, v148
	v_add_f32_e32 v149, 1.0, v149
	v_rcp_f32_e32 v148, v148
	v_rcp_f32_e32 v149, v149
	v_cvt_pk_bf16_f32 v244, v183, v187
	global_store_dwordx4 v[146:147], v[242:245], off offset:256
	v_pk_fma_f32 v[214:215], v[30:31], v[190:191], v[142:143] op_sel_hi:[1,0,1]
	v_lshl_add_u64 v[146:147], s[2:3], 0, v[204:205]
	v_cvt_pk_bf16_f32 v243, v148, v149
	v_pk_fma_f32 v[148:149], v[28:29], v[190:191], v[140:141] op_sel_hi:[1,0,1]
	v_mul_f32_e32 v183, 0xbfb8aa3b, v214
	v_mul_f32_e32 v187, 0xbfb8aa3b, v215
	v_mul_f32_e32 v148, 0xbfb8aa3b, v148
	v_mul_f32_e32 v149, 0xbfb8aa3b, v149
	v_exp_f32_e32 v183, v183
	v_exp_f32_e32 v187, v187
	v_exp_f32_e32 v148, v148
	v_exp_f32_e32 v149, v149
	v_add_f32_e32 v183, 1.0, v183
	v_add_f32_e32 v187, 1.0, v187
	v_add_f32_e32 v148, 1.0, v148
	v_add_f32_e32 v149, 1.0, v149
	v_rcp_f32_e32 v183, v183
	v_rcp_f32_e32 v187, v187
	v_rcp_f32_e32 v148, v148
	v_rcp_f32_e32 v149, v149
	v_pk_fma_f32 v[214:215], v[26:27], v[190:191], v[138:139] op_sel_hi:[1,0,1]
	v_cvt_pk_bf16_f32 v242, v183, v187
	v_mul_f32_e32 v183, 0xbfb8aa3b, v214
	v_mul_f32_e32 v187, 0xbfb8aa3b, v215
	v_cvt_pk_bf16_f32 v245, v148, v149
	v_pk_fma_f32 v[148:149], v[96:97], v[190:191], v[136:137] op_sel_hi:[1,0,1]
	v_exp_f32_e32 v183, v183
	v_exp_f32_e32 v187, v187
	v_mul_f32_e32 v148, 0xbfb8aa3b, v148
	v_mul_f32_e32 v149, 0xbfb8aa3b, v149
	v_exp_f32_e32 v148, v148
	v_exp_f32_e32 v149, v149
	v_add_f32_e32 v183, 1.0, v183
	v_add_f32_e32 v187, 1.0, v187
	v_rcp_f32_e32 v183, v183
	v_rcp_f32_e32 v187, v187
	v_add_f32_e32 v148, 1.0, v148
	v_add_f32_e32 v149, 1.0, v149
	v_rcp_f32_e32 v148, v148
	v_rcp_f32_e32 v149, v149
	v_lshl_add_u64 v[146:147], v[146:147], 0, v[0:1]
	v_cvt_pk_bf16_f32 v244, v183, v187
	global_store_dwordx4 v[146:147], v[242:245], off
	v_pk_fma_f32 v[214:215], v[94:95], v[190:191], v[134:135] op_sel_hi:[1,0,1]
	s_nop 0
	v_cvt_pk_bf16_f32 v243, v148, v149
	v_pk_fma_f32 v[148:149], v[92:93], v[190:191], v[132:133] op_sel_hi:[1,0,1]
	v_mul_f32_e32 v183, 0xbfb8aa3b, v214
	v_mul_f32_e32 v187, 0xbfb8aa3b, v215
	v_mul_f32_e32 v148, 0xbfb8aa3b, v148
	v_mul_f32_e32 v149, 0xbfb8aa3b, v149
	v_exp_f32_e32 v183, v183
	v_exp_f32_e32 v187, v187
	v_exp_f32_e32 v148, v148
	v_exp_f32_e32 v149, v149
	v_add_f32_e32 v183, 1.0, v183
	v_add_f32_e32 v187, 1.0, v187
	v_add_f32_e32 v148, 1.0, v148
	v_add_f32_e32 v149, 1.0, v149
	v_rcp_f32_e32 v183, v183
	v_rcp_f32_e32 v187, v187
	v_rcp_f32_e32 v148, v148
	v_rcp_f32_e32 v149, v149
	v_pk_fma_f32 v[214:215], v[90:91], v[190:191], v[130:131] op_sel_hi:[1,0,1]
	v_cvt_pk_bf16_f32 v242, v183, v187
	v_mul_f32_e32 v183, 0xbfb8aa3b, v214
	v_mul_f32_e32 v187, 0xbfb8aa3b, v215
	v_cvt_pk_bf16_f32 v245, v148, v149
	v_pk_fma_f32 v[148:149], v[24:25], v[194:195], v[144:145] op_sel_hi:[1,0,1]
	v_exp_f32_e32 v183, v183
	v_exp_f32_e32 v187, v187
	v_mul_f32_e32 v148, 0xbfb8aa3b, v148
	v_mul_f32_e32 v149, 0xbfb8aa3b, v149
	v_exp_f32_e32 v148, v148
	v_exp_f32_e32 v149, v149
	v_add_f32_e32 v183, 1.0, v183
	v_add_f32_e32 v187, 1.0, v187
	v_rcp_f32_e32 v183, v183
	v_rcp_f32_e32 v187, v187
	v_add_f32_e32 v148, 1.0, v148
	v_add_f32_e32 v149, 1.0, v149
	v_rcp_f32_e32 v148, v148
	v_rcp_f32_e32 v149, v149
	v_cvt_pk_bf16_f32 v244, v183, v187
	global_store_dwordx4 v[146:147], v[242:245], off offset:256
	v_pk_fma_f32 v[214:215], v[22:23], v[194:195], v[142:143] op_sel_hi:[1,0,1]
	v_lshl_add_u64 v[146:147], s[2:3], 0, v[202:203]
	v_cvt_pk_bf16_f32 v243, v148, v149
	v_pk_fma_f32 v[148:149], v[20:21], v[194:195], v[140:141] op_sel_hi:[1,0,1]
	v_mul_f32_e32 v183, 0xbfb8aa3b, v214
	v_mul_f32_e32 v187, 0xbfb8aa3b, v215
	v_mul_f32_e32 v148, 0xbfb8aa3b, v148
	v_mul_f32_e32 v149, 0xbfb8aa3b, v149
	v_exp_f32_e32 v183, v183
	v_exp_f32_e32 v187, v187
	v_exp_f32_e32 v148, v148
	v_exp_f32_e32 v149, v149
	v_add_f32_e32 v183, 1.0, v183
	v_add_f32_e32 v187, 1.0, v187
	v_add_f32_e32 v148, 1.0, v148
	v_add_f32_e32 v149, 1.0, v149
	v_rcp_f32_e32 v183, v183
	v_rcp_f32_e32 v187, v187
	v_rcp_f32_e32 v148, v148
	v_rcp_f32_e32 v149, v149
	v_pk_fma_f32 v[214:215], v[18:19], v[194:195], v[138:139] op_sel_hi:[1,0,1]
	v_cvt_pk_bf16_f32 v242, v183, v187
	v_mul_f32_e32 v183, 0xbfb8aa3b, v214
	v_mul_f32_e32 v187, 0xbfb8aa3b, v215
	v_cvt_pk_bf16_f32 v245, v148, v149
	v_pk_fma_f32 v[148:149], v[88:89], v[194:195], v[136:137] op_sel_hi:[1,0,1]
	v_exp_f32_e32 v183, v183
	v_exp_f32_e32 v187, v187
	v_mul_f32_e32 v148, 0xbfb8aa3b, v148
	v_mul_f32_e32 v149, 0xbfb8aa3b, v149
	v_exp_f32_e32 v148, v148
	v_exp_f32_e32 v149, v149
	v_add_f32_e32 v183, 1.0, v183
	v_add_f32_e32 v187, 1.0, v187
	v_rcp_f32_e32 v183, v183
	v_rcp_f32_e32 v187, v187
	v_add_f32_e32 v148, 1.0, v148
	v_add_f32_e32 v149, 1.0, v149
	v_rcp_f32_e32 v148, v148
	v_rcp_f32_e32 v149, v149
	v_lshl_add_u64 v[146:147], v[146:147], 0, v[0:1]
	v_cvt_pk_bf16_f32 v244, v183, v187
	global_store_dwordx4 v[146:147], v[242:245], off
	v_pk_fma_f32 v[214:215], v[86:87], v[194:195], v[134:135] op_sel_hi:[1,0,1]
	s_nop 0
	v_cvt_pk_bf16_f32 v243, v148, v149
	v_pk_fma_f32 v[148:149], v[84:85], v[194:195], v[132:133] op_sel_hi:[1,0,1]
	v_mul_f32_e32 v183, 0xbfb8aa3b, v214
	v_mul_f32_e32 v187, 0xbfb8aa3b, v215
	v_mul_f32_e32 v148, 0xbfb8aa3b, v148
	v_mul_f32_e32 v149, 0xbfb8aa3b, v149
	v_exp_f32_e32 v183, v183
	v_exp_f32_e32 v187, v187
	v_exp_f32_e32 v148, v148
	v_exp_f32_e32 v149, v149
	v_add_f32_e32 v183, 1.0, v183
	v_add_f32_e32 v187, 1.0, v187
	v_add_f32_e32 v148, 1.0, v148
	v_add_f32_e32 v149, 1.0, v149
	v_rcp_f32_e32 v183, v183
	v_rcp_f32_e32 v187, v187
	v_rcp_f32_e32 v148, v148
	v_rcp_f32_e32 v149, v149
	v_pk_fma_f32 v[214:215], v[82:83], v[194:195], v[130:131] op_sel_hi:[1,0,1]
	v_cvt_pk_bf16_f32 v242, v183, v187
	v_mul_f32_e32 v183, 0xbfb8aa3b, v214
	v_mul_f32_e32 v187, 0xbfb8aa3b, v215
	v_cvt_pk_bf16_f32 v245, v148, v149
	v_pk_fma_f32 v[148:149], v[16:17], v[198:199], v[144:145] op_sel_hi:[1,0,1]
	v_exp_f32_e32 v183, v183
	v_exp_f32_e32 v187, v187
	v_mul_f32_e32 v148, 0xbfb8aa3b, v148
	v_mul_f32_e32 v149, 0xbfb8aa3b, v149
	v_exp_f32_e32 v148, v148
	v_exp_f32_e32 v149, v149
	v_add_f32_e32 v183, 1.0, v183
	v_add_f32_e32 v187, 1.0, v187
	v_rcp_f32_e32 v183, v183
	v_rcp_f32_e32 v187, v187
	v_add_f32_e32 v148, 1.0, v148
	v_add_f32_e32 v149, 1.0, v149
	v_rcp_f32_e32 v148, v148
	v_rcp_f32_e32 v149, v149
	v_cvt_pk_bf16_f32 v244, v183, v187
	global_store_dwordx4 v[146:147], v[242:245], off offset:256
	v_pk_fma_f32 v[214:215], v[14:15], v[198:199], v[142:143] op_sel_hi:[1,0,1]
	v_lshlrev_b64 v[146:147], 11, v[192:193]
	v_cvt_pk_bf16_f32 v243, v148, v149
	v_pk_fma_f32 v[148:149], v[12:13], v[198:199], v[140:141] op_sel_hi:[1,0,1]
	v_mul_f32_e32 v183, 0xbfb8aa3b, v214
	v_mul_f32_e32 v187, 0xbfb8aa3b, v215
	v_mul_f32_e32 v148, 0xbfb8aa3b, v148
	v_mul_f32_e32 v149, 0xbfb8aa3b, v149
	v_exp_f32_e32 v183, v183
	v_exp_f32_e32 v187, v187
	v_exp_f32_e32 v148, v148
	v_exp_f32_e32 v149, v149
	v_add_f32_e32 v183, 1.0, v183
	v_add_f32_e32 v187, 1.0, v187
	v_add_f32_e32 v148, 1.0, v148
	v_add_f32_e32 v149, 1.0, v149
	v_rcp_f32_e32 v183, v183
	v_rcp_f32_e32 v187, v187
	v_rcp_f32_e32 v148, v148
	v_rcp_f32_e32 v149, v149
	v_pk_fma_f32 v[214:215], v[10:11], v[198:199], v[138:139] op_sel_hi:[1,0,1]
	v_cvt_pk_bf16_f32 v242, v183, v187
	v_mul_f32_e32 v183, 0xbfb8aa3b, v214
	v_mul_f32_e32 v187, 0xbfb8aa3b, v215
	v_cvt_pk_bf16_f32 v245, v148, v149
	v_pk_fma_f32 v[148:149], v[68:69], v[198:199], v[136:137] op_sel_hi:[1,0,1]
	v_exp_f32_e32 v183, v183
	v_exp_f32_e32 v187, v187
	v_mul_f32_e32 v148, 0xbfb8aa3b, v148
	v_mul_f32_e32 v149, 0xbfb8aa3b, v149
	v_exp_f32_e32 v148, v148
	v_exp_f32_e32 v149, v149
	v_add_f32_e32 v183, 1.0, v183
	v_add_f32_e32 v187, 1.0, v187
	v_rcp_f32_e32 v183, v183
	v_rcp_f32_e32 v187, v187
	v_add_f32_e32 v148, 1.0, v148
	v_add_f32_e32 v149, 1.0, v149
	v_rcp_f32_e32 v148, v148
	v_rcp_f32_e32 v149, v149
	v_lshl_add_u64 v[146:147], s[2:3], 0, v[146:147]
	v_pk_fma_f32 v[214:215], v[66:67], v[198:199], v[134:135] op_sel_hi:[1,0,1]
	v_lshl_add_u64 v[146:147], v[146:147], 0, v[0:1]
	v_cvt_pk_bf16_f32 v244, v183, v187
	v_mul_f32_e32 v183, 0xbfb8aa3b, v214
	v_mul_f32_e32 v187, 0xbfb8aa3b, v215
	global_store_dwordx4 v[146:147], v[242:245], off
	v_exp_f32_e32 v183, v183
	v_exp_f32_e32 v187, v187
	v_cvt_pk_bf16_f32 v243, v148, v149
	v_pk_fma_f32 v[148:149], v[60:61], v[198:199], v[132:133] op_sel_hi:[1,0,1]
	v_pk_fma_f32 v[142:143], v[6:7], v[200:201], v[142:143] op_sel_hi:[1,0,1]
	v_mul_f32_e32 v148, 0xbfb8aa3b, v148
	v_mul_f32_e32 v149, 0xbfb8aa3b, v149
	v_pk_fma_f32 v[134:135], v[46:47], v[200:201], v[134:135] op_sel_hi:[1,0,1]
	v_exp_f32_e32 v148, v148
	v_exp_f32_e32 v149, v149
	v_mul_f32_e32 v142, 0xbfb8aa3b, v142
	v_mul_f32_e32 v143, 0xbfb8aa3b, v143
	v_mul_f32_e32 v134, 0xbfb8aa3b, v134
	v_mul_f32_e32 v135, 0xbfb8aa3b, v135
	v_exp_f32_e32 v142, v142
	v_exp_f32_e32 v143, v143
	v_exp_f32_e32 v134, v134
	v_exp_f32_e32 v135, v135
	v_add_f32_e32 v183, 1.0, v183
	v_add_f32_e32 v187, 1.0, v187
	v_rcp_f32_e32 v183, v183
	v_rcp_f32_e32 v187, v187
	v_add_f32_e32 v148, 1.0, v148
	v_add_f32_e32 v149, 1.0, v149
	v_rcp_f32_e32 v148, v148
	v_rcp_f32_e32 v149, v149
	v_add_f32_e32 v142, 1.0, v142
	v_add_f32_e32 v143, 1.0, v143
	v_add_f32_e32 v134, 1.0, v134
	v_add_f32_e32 v135, 1.0, v135
	v_pk_fma_f32 v[214:215], v[58:59], v[198:199], v[130:131] op_sel_hi:[1,0,1]
	v_rcp_f32_e32 v142, v142
	v_rcp_f32_e32 v143, v143
	v_rcp_f32_e32 v134, v134
	v_rcp_f32_e32 v135, v135
	v_cvt_pk_bf16_f32 v242, v183, v187
	v_mul_f32_e32 v183, 0xbfb8aa3b, v214
	v_mul_f32_e32 v187, 0xbfb8aa3b, v215
	v_exp_f32_e32 v183, v183
	v_exp_f32_e32 v187, v187
	v_cvt_pk_bf16_f32 v245, v148, v149
	v_pk_fma_f32 v[148:149], v[8:9], v[200:201], v[144:145] op_sel_hi:[1,0,1]
	v_pk_fma_f32 v[138:139], v[2:3], v[200:201], v[138:139] op_sel_hi:[1,0,1]
	v_pk_fma_f32 v[136:137], v[48:49], v[200:201], v[136:137] op_sel_hi:[1,0,1]
	v_pk_fma_f32 v[130:131], v[38:39], v[200:201], v[130:131] op_sel_hi:[1,0,1]
	v_cvt_pk_bf16_f32 v144, v142, v143
	v_mul_f32_e32 v142, 0xbfb8aa3b, v148
	v_mul_f32_e32 v143, 0xbfb8aa3b, v149
	v_mul_f32_e32 v138, 0xbfb8aa3b, v138
	v_mul_f32_e32 v139, 0xbfb8aa3b, v139
	v_cvt_pk_bf16_f32 v134, v134, v135
	v_mul_f32_e32 v135, 0xbfb8aa3b, v136
	v_mul_f32_e32 v136, 0xbfb8aa3b, v137
	v_mul_f32_e32 v130, 0xbfb8aa3b, v130
	v_mul_f32_e32 v131, 0xbfb8aa3b, v131
	v_exp_f32_e32 v142, v142
	v_exp_f32_e32 v143, v143
	v_exp_f32_e32 v138, v138
	v_exp_f32_e32 v139, v139
	v_exp_f32_e32 v135, v135
	v_exp_f32_e32 v136, v136
	v_exp_f32_e32 v130, v130
	v_exp_f32_e32 v131, v131
	v_add_f32_e32 v183, 1.0, v183
	v_add_f32_e32 v187, 1.0, v187
	v_rcp_f32_e32 v183, v183
	v_rcp_f32_e32 v187, v187
	v_add_f32_e32 v142, 1.0, v142
	v_add_f32_e32 v143, 1.0, v143
	v_add_f32_e32 v138, 1.0, v138
	v_add_f32_e32 v139, 1.0, v139
	v_add_f32_e32 v135, 1.0, v135
	v_add_f32_e32 v136, 1.0, v136
	v_add_f32_e32 v130, 1.0, v130
	v_add_f32_e32 v131, 1.0, v131
	v_rcp_f32_e32 v142, v142
	v_rcp_f32_e32 v143, v143
	v_rcp_f32_e32 v138, v138
	v_rcp_f32_e32 v139, v139
	v_rcp_f32_e32 v135, v135
	v_rcp_f32_e32 v136, v136
	v_rcp_f32_e32 v130, v130
	v_rcp_f32_e32 v131, v131
	v_cvt_pk_bf16_f32 v244, v183, v187
	global_store_dwordx4 v[146:147], v[242:245], off offset:256
	v_lshlrev_b64 v[146:147], 11, v[196:197]
	v_lshl_add_u64 v[146:147], s[2:3], 0, v[146:147]
	v_pk_fma_f32 v[140:141], v[4:5], v[200:201], v[140:141] op_sel_hi:[1,0,1]
	v_pk_fma_f32 v[132:133], v[40:41], v[200:201], v[132:133] op_sel_hi:[1,0,1]
	v_cvt_pk_bf16_f32 v145, v142, v143
	v_lshl_add_u64 v[142:143], v[146:147], 0, v[0:1]
	v_cvt_pk_bf16_f32 v146, v138, v139
	v_mul_f32_e32 v138, 0xbfb8aa3b, v140
	v_mul_f32_e32 v139, 0xbfb8aa3b, v141
	v_cvt_pk_bf16_f32 v135, v135, v136
	v_cvt_pk_bf16_f32 v136, v130, v131
	v_mul_f32_e32 v130, 0xbfb8aa3b, v132
	v_mul_f32_e32 v131, 0xbfb8aa3b, v133
	v_exp_f32_e32 v138, v138
	v_exp_f32_e32 v139, v139
	v_exp_f32_e32 v130, v130
	v_exp_f32_e32 v131, v131
	v_add_f32_e32 v138, 1.0, v138
	v_add_f32_e32 v139, 1.0, v139
	v_add_f32_e32 v130, 1.0, v130
	v_add_f32_e32 v131, 1.0, v131
	v_rcp_f32_e32 v138, v138
	v_rcp_f32_e32 v139, v139
	v_rcp_f32_e32 v130, v130
	v_rcp_f32_e32 v131, v131
	v_cvt_pk_bf16_f32 v147, v138, v139
	global_store_dwordx4 v[142:143], v[144:147], off
	v_cvt_pk_bf16_f32 v137, v130, v131
	global_store_dwordx4 v[142:143], v[134:137], off offset:256
	s_cbranch_execnz .LBB0_181

.LBB0_272:
	v_mov_b32_e32 v0, s90
	s_waitcnt lgkmcnt(0)
	s_barrier
	v_add_u32_e32 v178, s6, v112
	v_ashrrev_i32_e32 v179, 31, v178
	v_lshlrev_b64 v[178:179], 11, v[178:179]
	v_lshl_add_u64 v[178:179], v[80:81], 0, v[178:179]
	global_load_dwordx2 v[170:171], v[178:179], off
	global_load_dwordx2 v[172:173], v[178:179], off offset:32
	global_load_dwordx2 v[174:175], v[178:179], off offset:64
	global_load_dwordx2 v[176:177], v[178:179], off offset:96
	ds_read_b32 v0, v0 offset:512
	s_add_i32 s0, s7, s6
	s_orn2_b32 s16, 0xffffe03f, s0
	v_cmp_lt_i32_e32 vcc, s16, v99
	v_mov_b32_e32 v43, 0
	v_mov_b32_e32 v42, 0
	s_and_saveexec_b64 s[0:1], vcc
	s_cbranch_execz .LBB0_274
	v_add3_u32 v34, v111, s6, -3
	v_ashrrev_i32_e32 v35, 31, v34
	v_lshlrev_b64 v[34:35], 11, v[34:35]
	v_lshl_add_u64 v[34:35], v[78:79], 0, v[34:35]
	global_load_ushort v42, v[34:35], off
.LBB0_274:
	s_or_b64 exec, exec, s[0:1]
	v_cmp_lt_i32_e32 vcc, s16, v104
	s_and_saveexec_b64 s[0:1], vcc
	s_cbranch_execz .LBB0_276
	v_add3_u32 v34, v111, s6, -2
	v_ashrrev_i32_e32 v35, 31, v34
	v_lshlrev_b64 v[34:35], 11, v[34:35]
	v_lshl_add_u64 v[34:35], v[78:79], 0, v[34:35]
	global_load_ushort v43, v[34:35], off
.LBB0_276:
	s_or_b64 exec, exec, s[0:1]
	v_cmp_ge_i32_e32 vcc, s16, v105
	v_add_u32_e32 v34, s6, v111
	s_and_saveexec_b64 s[0:1], vcc
	s_xor_b64 s[0:1], exec, s[0:1]
	v_add_u32_e32 v34, s6, v111
	s_or_saveexec_b64 s[0:1], s[0:1]
	v_mov_b32_e32 v126, 0
	v_mov_b32_e32 v47, 0
	s_xor_b64 exec, exec, s[0:1]
	s_cbranch_execz .LBB0_280
	v_add_u32_e32 v36, -1, v34
	v_ashrrev_i32_e32 v37, 31, v36
	v_lshlrev_b64 v[36:37], 11, v[36:37]
	v_lshl_add_u64 v[36:37], v[78:79], 0, v[36:37]
	global_load_ushort v47, v[36:37], off
.LBB0_280:
	s_or_b64 exec, exec, s[0:1]
	v_add_u32_e32 v58, 6, v34
	v_add_u32_e32 v62, 8, v34
	v_add_u32_e32 v64, 9, v34
	v_add_u32_e32 v88, 11, v34
	v_add_u32_e32 v90, 12, v34
	v_add_u32_e32 v92, 13, v34
	v_add_u32_e32 v128, 14, v34
	v_add_u32_e32 v130, 15, v34
	v_ashrrev_i32_e32 v35, 31, v34
	v_add_u32_e32 v48, 1, v34
	v_add_u32_e32 v60, 7, v34
	v_add_u32_e32 v86, 10, v34
	v_ashrrev_i32_e32 v59, 31, v58
	v_ashrrev_i32_e32 v63, 31, v62
	v_ashrrev_i32_e32 v65, 31, v64
	v_ashrrev_i32_e32 v89, 31, v88
	v_ashrrev_i32_e32 v91, 31, v90
	v_ashrrev_i32_e32 v93, 31, v92
	v_ashrrev_i32_e32 v129, 31, v128
	v_ashrrev_i32_e32 v131, 31, v130
	v_lshlrev_b64 v[36:37], 11, v[34:35]
	v_ashrrev_i32_e32 v49, 31, v48
	v_ashrrev_i32_e32 v61, 31, v60
	v_ashrrev_i32_e32 v87, 31, v86
	v_lshlrev_b64 v[62:63], 11, v[62:63]
	v_lshlrev_b64 v[64:65], 11, v[64:65]
	v_lshlrev_b64 v[88:89], 11, v[88:89]
	v_lshlrev_b64 v[90:91], 11, v[90:91]
	v_lshlrev_b64 v[92:93], 11, v[92:93]
	v_lshlrev_b64 v[128:129], 11, v[128:129]
	v_lshlrev_b64 v[130:131], 11, v[130:131]
	v_lshlrev_b64 v[58:59], 11, v[58:59]
	v_lshl_add_u64 v[36:37], v[78:79], 0, v[36:37]
	v_lshlrev_b64 v[48:49], 11, v[48:49]
	v_lshlrev_b64 v[60:61], 11, v[60:61]
	v_lshlrev_b64 v[86:87], 11, v[86:87]
	v_lshl_add_u64 v[88:89], v[78:79], 0, v[88:89]
	v_lshl_add_u64 v[90:91], v[78:79], 0, v[90:91]
	v_lshl_add_u64 v[92:93], v[78:79], 0, v[92:93]
	v_lshl_add_u64 v[128:129], v[78:79], 0, v[128:129]
	v_lshl_add_u64 v[130:131], v[78:79], 0, v[130:131]
	v_lshl_add_u64 v[64:65], v[78:79], 0, v[64:65]
	v_lshl_add_u64 v[62:63], v[78:79], 0, v[62:63]
	v_lshl_add_u64 v[58:59], v[78:79], 0, v[58:59]
	global_load_ushort v127, v[36:37], off
	v_add_u32_e32 v50, 2, v34
	v_add_u32_e32 v52, 3, v34
	v_add_u32_e32 v54, 4, v34
	v_add_u32_e32 v56, 5, v34
	ds_read_b128 v[38:41], v106
	ds_read_b128 v[34:37], v106 offset:16
	global_load_ushort v88, v[88:89], off
	s_nop 0
	global_load_ushort v89, v[90:91], off
	s_nop 0
	global_load_ushort v90, v[92:93], off
	global_load_ushort v91, v[128:129], off
	s_nop 0
	global_load_ushort v92, v[130:131], off
	v_lshl_add_u64 v[86:87], v[78:79], 0, v[86:87]
	global_load_ushort v93, v[64:65], off
	global_load_ushort v128, v[86:87], off
	v_lshl_add_u64 v[60:61], v[78:79], 0, v[60:61]
	global_load_ushort v129, v[62:63], off
	global_load_ushort v130, v[60:61], off
	v_lshl_add_u64 v[48:49], v[78:79], 0, v[48:49]
	global_load_ushort v131, v[58:59], off
	global_load_ushort v132, v[48:49], off
	v_ashrrev_i32_e32 v53, 31, v52
	v_ashrrev_i32_e32 v55, 31, v54
	v_ashrrev_i32_e32 v57, 31, v56
	v_ashrrev_i32_e32 v51, 31, v50
	v_lshlrev_b64 v[48:49], 11, v[52:53]
	v_lshlrev_b64 v[52:53], 11, v[54:55]
	v_lshlrev_b64 v[54:55], 11, v[56:57]
	v_lshlrev_b64 v[50:51], 11, v[50:51]
	v_lshl_add_u64 v[54:55], v[78:79], 0, v[54:55]
	v_lshl_add_u64 v[50:51], v[78:79], 0, v[50:51]
	v_lshl_add_u64 v[48:49], v[78:79], 0, v[48:49]
	v_lshl_add_u64 v[52:53], v[78:79], 0, v[52:53]
	global_load_ushort v133, v[54:55], off
	global_load_ushort v147, v[48:49], off
	global_load_ushort v134, v[52:53], off
	global_load_ushort v156, v[50:51], off
	s_waitcnt lgkmcnt(0)
	v_sub_f32_e32 v34, v0, v34
	v_mul_f32_e32 v34, 0x3fb8aa3b, v34
	v_exp_f32_e32 v140, v34
	v_sub_f32_e32 v34, v0, v35
	v_mul_f32_e32 v34, 0x3fb8aa3b, v34
	ds_read_b128 v[50:53], v106 offset:32
	ds_read_b128 v[58:61], v106 offset:48
	v_exp_f32_e32 v141, v34
	v_sub_f32_e32 v34, v0, v36
	v_mul_f32_e32 v34, 0x3fb8aa3b, v34
	v_exp_f32_e32 v86, v34
	v_sub_f32_e32 v34, v0, v37
	v_mul_f32_e32 v34, 0x3fb8aa3b, v34
	v_exp_f32_e32 v87, v34
	s_waitcnt lgkmcnt(1)
	v_sub_f32_e32 v34, v0, v50
	v_mul_f32_e32 v34, 0x3fb8aa3b, v34
	v_exp_f32_e32 v56, v34
	v_sub_f32_e32 v34, v0, v51
	v_mul_f32_e32 v34, 0x3fb8aa3b, v34
	v_exp_f32_e32 v57, v34
	v_sub_f32_e32 v34, v0, v52
	s_waitcnt vmcnt(16)
	v_lshlrev_b32_e32 v42, 16, v42
	v_lshlrev_b32_e32 v43, 16, v43
	v_lshlrev_b32_e32 v47, 16, v47
	v_mov_b32_e32 v46, v43
	v_mul_f32_e32 v34, 0x3fb8aa3b, v34
	v_pk_fma_f32 v[42:43], v[68:69], v[42:43], v[76:77]
	v_exp_f32_e32 v54, v34
	v_sub_f32_e32 v34, v0, v53
	v_pk_fma_f32 v[42:43], v[70:71], v[46:47], v[42:43]
	v_mov_b32_e32 v48, v47
	v_mul_f32_e32 v34, 0x3fb8aa3b, v34
	v_sub_f32_e32 v38, v0, v38
	v_exp_f32_e32 v55, v34
	s_waitcnt lgkmcnt(0)
	v_sub_f32_e32 v34, v0, v58
	v_mul_f32_e32 v38, 0x3fb8aa3b, v38
	v_mul_f32_e32 v34, 0x3fb8aa3b, v34
	v_exp_f32_e32 v136, v38
	v_sub_f32_e32 v38, v0, v39
	v_exp_f32_e32 v50, v34
	v_sub_f32_e32 v34, v0, v59
	v_mul_f32_e32 v38, 0x3fb8aa3b, v38
	v_mul_f32_e32 v34, 0x3fb8aa3b, v34
	v_exp_f32_e32 v137, v38
	v_sub_f32_e32 v38, v0, v40
	v_exp_f32_e32 v51, v34
	v_sub_f32_e32 v34, v0, v60
	v_mul_f32_e32 v38, 0x3fb8aa3b, v38
	v_mul_f32_e32 v34, 0x3fb8aa3b, v34
	v_exp_f32_e32 v138, v38
	v_sub_f32_e32 v38, v0, v41
	v_exp_f32_e32 v52, v34
	v_sub_f32_e32 v34, v0, v61
	v_mul_f32_e32 v38, 0x3fb8aa3b, v38
	v_mul_f32_e32 v34, 0x3fb8aa3b, v34
	v_exp_f32_e32 v139, v38
	v_exp_f32_e32 v53, v34
	ds_read_b128 v[34:37], v106 offset:304
	ds_read_b128 v[38:41], v106 offset:288
	s_waitcnt vmcnt(15)
	v_lshlrev_b32_e32 v49, 16, v127
	v_pk_fma_f32 v[42:43], v[72:73], v[48:49], v[42:43]
	v_mov_b32_e32 v46, v49
	v_pk_fma_f32 v[48:49], v[68:69], v[48:49], v[76:77]
	s_waitcnt vmcnt(12)
	v_lshlrev_b32_e32 v63, 16, v90
	s_waitcnt vmcnt(11)
	v_lshlrev_b32_e32 v65, 16, v91
	s_waitcnt vmcnt(10)
	v_lshlrev_b32_e32 v61, 16, v92
	s_waitcnt vmcnt(9)
	v_lshlrev_b32_e32 v90, 16, v93
	s_waitcnt vmcnt(8)
	v_lshlrev_b32_e32 v91, 16, v128
	s_waitcnt vmcnt(7)
	v_lshlrev_b32_e32 v143, 16, v129
	s_waitcnt vmcnt(6)
	v_lshlrev_b32_e32 v142, 16, v130
	s_waitcnt vmcnt(5)
	v_lshlrev_b32_e32 v145, 16, v131
	s_waitcnt vmcnt(4)
	v_lshlrev_b32_e32 v146, 16, v132
	v_mov_b32_e32 v47, v146
	v_pk_fma_f32 v[42:43], v[74:75], v[46:47], v[42:43]
	v_pk_fma_f32 v[46:47], v[70:71], v[46:47], v[48:49]
	v_mul_f32_e32 v127, 0xbfb8aa3b, v42
	v_exp_f32_e32 v127, v127
	v_mul_f32_e32 v128, 0xbfb8aa3b, v43
	v_exp_f32_e32 v150, v128
	v_pk_fma_f32 v[92:93], v[68:69], v[142:143], v[76:77]
	v_add_f32_e32 v127, 1.0, v127
	v_rcp_f32_e32 v152, v127
	v_add_f32_e32 v127, 1.0, v150
	s_waitcnt vmcnt(3)
	v_lshlrev_b32_e32 v144, 16, v133
	s_waitcnt vmcnt(1)
	v_lshlrev_b32_e32 v151, 16, v134
	ds_read_b128 v[128:131], v106 offset:272
	ds_read_b128 v[132:135], v106 offset:256
	v_rcp_f32_e32 v153, v127
	v_lshlrev_b32_e32 v150, 16, v147
	s_waitcnt vmcnt(0)
	v_lshlrev_b32_e32 v147, 16, v156
	v_pk_fma_f32 v[46:47], v[72:73], v[146:147], v[46:47]
	v_pk_mul_f32 v[42:43], v[42:43], v[152:153]
	v_pk_fma_f32 v[154:155], v[68:69], v[150:151], v[76:77]
	s_waitcnt lgkmcnt(0)
	v_pk_mul_f32 v[42:43], v[42:43], v[132:133]
	v_pk_mov_b32 v[132:133], v[146:147], v[150:151] op_sel:[1,0]
	v_pk_mul_f32 v[136:137], v[42:43], v[136:137]
	v_pk_fma_f32 v[48:49], v[74:75], v[132:133], v[46:47]
	v_pk_fma_f32 v[148:149], v[68:69], v[144:145], v[76:77]
	v_mul_f32_e32 v46, 0xbfb8aa3b, v48
	v_exp_f32_e32 v46, v46
	v_mul_f32_e32 v47, 0xbfb8aa3b, v49
	v_exp_f32_e32 v47, v47
	v_lshlrev_b64 v[44:45], 11, v[44:45]
	v_add_f32_e32 v46, 1.0, v46
	v_rcp_f32_e32 v152, v46
	v_add_f32_e32 v46, 1.0, v47
	v_rcp_f32_e32 v153, v46
	v_cvt_pk_bf16_f32 v46, v42, v43
	v_cvt_pk_bf16_f32 v42, v136, v137
	v_pk_fma_f32 v[136:137], v[68:69], v[146:147], v[76:77]
	v_pk_mov_b32 v[146:147], v[150:151], v[144:145] op_sel:[1,0]
	v_pk_fma_f32 v[132:133], v[70:71], v[132:133], v[136:137]
	v_pk_mul_f32 v[48:49], v[48:49], v[152:153]
	v_pk_fma_f32 v[132:133], v[72:73], v[150:151], v[132:133]
	v_pk_mul_f32 v[48:49], v[48:49], v[134:135]
	v_pk_fma_f32 v[132:133], v[74:75], v[146:147], v[132:133]
	v_pk_mul_f32 v[136:137], v[48:49], v[138:139]
	v_mul_f32_e32 v43, 0xbfb8aa3b, v132
	v_exp_f32_e32 v43, v43
	v_mul_f32_e32 v47, 0xbfb8aa3b, v133
	v_exp_f32_e32 v47, v47
	v_lshlrev_b32_e32 v58, 16, v88
	v_add_f32_e32 v43, 1.0, v43
	v_rcp_f32_e32 v134, v43
	v_add_f32_e32 v43, 1.0, v47
	v_rcp_f32_e32 v135, v43
	v_cvt_pk_bf16_f32 v47, v48, v49
	v_cvt_pk_bf16_f32 v43, v136, v137
	v_lshlrev_b32_e32 v59, 16, v89
	v_pk_mul_f32 v[48:49], v[132:133], v[134:135]
	v_pk_fma_f32 v[134:135], v[70:71], v[146:147], v[154:155]
	v_pk_mov_b32 v[132:133], v[144:145], v[142:143] op_sel:[1,0]
	v_pk_fma_f32 v[134:135], v[72:73], v[144:145], v[134:135]
	v_pk_mul_f32 v[48:49], v[48:49], v[128:129]
	v_pk_fma_f32 v[136:137], v[74:75], v[132:133], v[134:135]
	v_pk_fma_f32 v[132:133], v[70:71], v[132:133], v[148:149]
	v_mul_f32_e32 v127, 0xbfb8aa3b, v136
	v_exp_f32_e32 v127, v127
	v_mul_f32_e32 v134, 0xbfb8aa3b, v137
	v_exp_f32_e32 v134, v134
	v_pk_mul_f32 v[128:129], v[48:49], v[140:141]
	v_pk_mov_b32 v[140:141], v[142:143], v[90:91] op_sel:[1,0]
	v_pk_fma_f32 v[142:143], v[72:73], v[142:143], v[132:133]
	v_cvt_pk_bf16_f32 v48, v48, v49
	v_add_f32_e32 v49, 1.0, v127
	v_pk_fma_f32 v[142:143], v[74:75], v[140:141], v[142:143]
	v_rcp_f32_e32 v138, v49
	v_add_f32_e32 v49, 1.0, v134
	v_lshl_add_u64 v[144:145], s[14:15], 0, v[44:45]
	v_mul_f32_e32 v44, 0xbfb8aa3b, v142
	v_rcp_f32_e32 v139, v49
	v_exp_f32_e32 v45, v44
	v_mul_f32_e32 v49, 0xbfb8aa3b, v143
	v_exp_f32_e32 v49, v49
	v_lshl_add_u64 v[146:147], v[82:83], 1, v[144:145]
	v_cvt_pk_bf16_f32 v44, v128, v129
	v_pk_mul_f32 v[128:129], v[136:137], v[138:139]
	v_add_f32_e32 v45, 1.0, v45
	global_load_dwordx4 v[132:135], v[146:147], off
	v_pk_mul_f32 v[148:149], v[128:129], v[130:131]
	global_load_dwordx4 v[128:131], v[146:147], off offset:1024
	v_rcp_f32_e32 v146, v45
	v_add_f32_e32 v45, 1.0, v49
	v_rcp_f32_e32 v147, v45
	v_lshl_add_u64 v[144:145], v[84:85], 1, v[144:145]
	global_load_dwordx4 v[136:139], v[144:145], off
	v_pk_mul_f32 v[86:87], v[148:149], v[86:87]
	v_pk_fma_f32 v[92:93], v[70:71], v[140:141], v[92:93]
	v_cvt_pk_bf16_f32 v45, v86, v87
	v_pk_mul_f32 v[86:87], v[142:143], v[146:147]
	global_load_dwordx4 v[140:143], v[144:145], off offset:1024
	v_pk_fma_f32 v[88:89], v[68:69], v[90:91], v[76:77]
	v_pk_mov_b32 v[146:147], v[90:91], v[58:59] op_sel:[1,0]
	v_pk_fma_f32 v[90:91], v[72:73], v[90:91], v[92:93]
	v_pk_fma_f32 v[88:89], v[70:71], v[146:147], v[88:89]
	v_pk_fma_f32 v[90:91], v[74:75], v[146:147], v[90:91]
	v_mov_b32_e32 v62, v59
	v_mul_f32_e32 v92, 0xbfb8aa3b, v90
	v_mul_f32_e32 v93, 0xbfb8aa3b, v91
	v_exp_f32_e32 v92, v92
	v_exp_f32_e32 v93, v93
	v_pk_mul_f32 v[38:39], v[86:87], v[38:39]
	v_pk_fma_f32 v[88:89], v[72:73], v[58:59], v[88:89]
	v_add_f32_e32 v86, 1.0, v92
	v_add_f32_e32 v87, 1.0, v93
	v_rcp_f32_e32 v86, v86
	v_rcp_f32_e32 v87, v87
	v_pk_fma_f32 v[88:89], v[74:75], v[62:63], v[88:89]
	v_pk_mul_f32 v[56:57], v[38:39], v[56:57]
	v_cvt_pk_bf16_f32 v38, v38, v39
	v_mul_f32_e32 v39, 0xbfb8aa3b, v88
	v_cvt_pk_bf16_f32 v56, v56, v57
	v_exp_f32_e32 v39, v39
	v_mul_f32_e32 v57, 0xbfb8aa3b, v89
	v_exp_f32_e32 v57, v57
	v_pk_mul_f32 v[86:87], v[90:91], v[86:87]
	v_add_f32_e32 v39, 1.0, v39
	v_pk_mul_f32 v[40:41], v[86:87], v[40:41]
	v_rcp_f32_e32 v86, v39
	v_pk_mul_f32 v[54:55], v[40:41], v[54:55]
	v_add_f32_e32 v39, 1.0, v57
	v_cvt_pk_bf16_f32 v57, v54, v55
	v_pk_fma_f32 v[54:55], v[68:69], v[58:59], v[76:77]
	v_mov_b32_e32 v64, v63
	v_pk_fma_f32 v[54:55], v[70:71], v[62:63], v[54:55]
	v_mov_b32_e32 v60, v65
	v_pk_fma_f32 v[54:55], v[72:73], v[64:65], v[54:55]
	v_rcp_f32_e32 v87, v39
	v_pk_fma_f32 v[54:55], v[74:75], v[60:61], v[54:55]
	v_cvt_pk_bf16_f32 v39, v40, v41
	v_mul_f32_e32 v58, 0xbfb8aa3b, v54
	v_exp_f32_e32 v58, v58
	v_mul_f32_e32 v59, 0xbfb8aa3b, v55
	v_exp_f32_e32 v59, v59
	v_pk_mul_f32 v[40:41], v[88:89], v[86:87]
	v_cvt_pk_bf16_f32 v49, v148, v149
	v_pk_mul_f32 v[34:35], v[40:41], v[34:35]
	v_add_f32_e32 v40, 1.0, v58
	v_rcp_f32_e32 v60, v40
	v_add_f32_e32 v40, 1.0, v59
	v_rcp_f32_e32 v61, v40
	v_pk_mul_f32 v[50:51], v[34:35], v[50:51]
	v_cvt_pk_bf16_f32 v40, v34, v35
	v_cvt_pk_bf16_f32 v58, v50, v51
	v_pk_mul_f32 v[34:35], v[54:55], v[60:61]
	s_nop 0
	v_pk_mul_f32 v[34:35], v[34:35], v[36:37]
	s_nop 0
	v_pk_mul_f32 v[36:37], v[34:35], v[52:53]
	v_cvt_pk_bf16_f32 v41, v34, v35
	v_add_u32_e32 v34, v100, v107
	v_cvt_pk_bf16_f32 v59, v36, v37
	ds_write_b128 v114, v[46:49] offset:1024
	ds_write_b128 v114, v[38:41] offset:1040
	ds_write_b128 v114, v[42:45] offset:10240
	ds_write_b128 v114, v[56:59] offset:10256
	s_waitcnt vmcnt(3)
	ds_write_b128 v34, v[132:135]
	ds_write_b16 v115, v132
	ds_write_b16_d16_hi v115, v132 offset:144
	ds_write_b16 v115, v133 offset:288
	ds_write_b16_d16_hi v115, v133 offset:432
	ds_write_b16 v115, v134 offset:576
	ds_write_b16_d16_hi v115, v134 offset:720
	ds_write_b16 v115, v135 offset:864
	ds_write_b16_d16_hi v115, v135 offset:1008
	v_add_u32_e32 v34, v101, v107
	s_waitcnt vmcnt(2)
	ds_write_b128 v34, v[128:131]
	v_add_u32_e32 v34, v100, v108
	s_waitcnt vmcnt(1)
	ds_write_b128 v34, v[136:139]
	ds_write_b16 v116, v136
	ds_write_b16_d16_hi v116, v136 offset:144
	ds_write_b16 v116, v137 offset:288
	ds_write_b16_d16_hi v116, v137 offset:432
	ds_write_b16 v116, v138 offset:576
	ds_write_b16_d16_hi v116, v138 offset:720
	ds_write_b16 v116, v139 offset:864
	ds_write_b16_d16_hi v116, v139 offset:1008
	v_add_u32_e32 v34, v101, v108
	s_waitcnt vmcnt(0)
	ds_write_b128 v34, v[140:143]
	s_waitcnt lgkmcnt(0)
	s_barrier
	ds_read_b128 v[34:37], v122
	ds_read_b128 v[38:41], v122 offset:64
	ds_read_b128 v[42:45], v123
	ds_read_b128 v[46:49], v123 offset:64
	s_waitcnt lgkmcnt(1)
	v_mfma_f32_16x16x32_bf16 v[34:37], v[34:37], v[42:45], 0
	ds_read_b128 v[42:45], v122 offset:128
	s_waitcnt lgkmcnt(1)
	v_mfma_f32_16x16x32_bf16 v[34:37], v[38:41], v[46:49], v[34:37]
	ds_read_b128 v[38:41], v122 offset:192
	ds_read_b128 v[46:49], v123 offset:128
	ds_read_b128 v[50:53], v123 offset:192
	ds_read2st64_b32 v[86:87], v102 offset1:1
	s_waitcnt lgkmcnt(2)
	v_mfma_f32_16x16x32_bf16 v[34:37], v[42:45], v[46:49], v[34:37]
	s_waitcnt lgkmcnt(1)
	v_mfma_f32_16x16x32_bf16 v[34:37], v[38:41], v[50:53], v[34:37]
	s_and_saveexec_b64 s[0:1], s[20:21]
	s_cbranch_execz .LBB0_282
	ds_read_b32 v38, v109
	s_waitcnt lgkmcnt(0)
	v_sub_f32_e32 v38, v86, v38
	v_mul_f32_e32 v38, 0x3fb8aa3b, v38
	v_exp_f32_e32 v38, v38
	s_nop 0
	v_mul_f32_e32 v126, v34, v38

.LBB0_312:
	s_or_b64 exec, exec, s[0:1]
	v_add_f32_e32 v48, v87, v47
	v_cndmask_b32_e64 v47, v47, v48, s[80:81]
	v_add_f32_e32 v48, v87, v50
	v_cndmask_b32_e64 v48, v50, v48, s[72:73]
	v_mul_f32_e32 v50, 0x3fb8aa3b, v86
	v_exp_f32_e32 v60, v50
	v_add_f32_e32 v49, v87, v88
	v_cndmask_b32_e64 v49, v88, v49, s[76:77]
	v_pk_mul_f32 v[50:51], v[60:61], v[42:43] op_sel_hi:[0,1]
	v_add_f32_e32 v42, v87, v46
	v_cndmask_b32_e64 v43, v46, v42, s[84:85]
	v_cvt_pk_bf16_f32 v42, v48, v49
	v_cvt_pk_bf16_f32 v43, v47, v43
	ds_write_b64 v119, v[42:43] offset:19456
	v_pk_mul_f32 v[52:53], v[60:61], v[44:45] op_sel_hi:[0,1]
	ds_read_b128 v[42:45], v124 offset:41728
	ds_read_b128 v[46:49], v123
	s_waitcnt lgkmcnt(0)
	v_mfma_f32_16x16x32_bf16 v[42:45], v[42:45], v[46:49], 0
	ds_read_b128 v[46:49], v124 offset:41792
	ds_read_b128 v[54:57], v123 offset:64
	s_waitcnt lgkmcnt(0)
	v_mfma_f32_16x16x32_bf16 v[42:45], v[46:49], v[54:57], v[42:45]
	ds_read_b128 v[46:49], v124 offset:41856
	ds_read_b128 v[54:57], v123 offset:128
	s_waitcnt lgkmcnt(0)
	v_mfma_f32_16x16x32_bf16 v[42:45], v[46:49], v[54:57], v[42:45]
	ds_read_b128 v[46:49], v124 offset:41920
	ds_read_b128 v[54:57], v123 offset:192
	s_waitcnt lgkmcnt(0)
	s_barrier
	v_mfma_f32_16x16x32_bf16 v[42:45], v[46:49], v[54:57], v[42:45]
	v_add_u32_e32 v46, s6, v112
	v_ashrrev_i32_e32 v47, 31, v46
	v_lshlrev_b64 v[48:49], 11, v[46:47]
	v_lshl_add_u64 v[54:55], v[80:81], 0, v[48:49]
	v_mov_b32_e32 v130, v170
	v_mov_b32_e32 v131, v171
	v_mov_b32_e32 v64, v172
	v_mov_b32_e32 v65, v173
	v_mov_b32_e32 v62, v174
	v_mov_b32_e32 v63, v175
	v_mov_b32_e32 v58, v176
	v_mov_b32_e32 v59, v177
	v_and_b32_e32 v49, 64, v220
	v_xor_b32_e32 v48, 16, v220
	v_add_u32_e32 v49, 64, v49
	v_cmp_lt_i32_e32 vcc, v48, v49
	v_lshl_add_u64 v[56:57], v[46:47], 4, s[2:3]
	s_nop 0
	v_cndmask_b32_e32 v48, v220, v48, vcc
	v_lshlrev_b32_e32 v92, 2, v48
	v_xor_b32_e32 v48, 32, v220
	v_cmp_lt_i32_e32 vcc, v48, v49
	s_nop 1
	v_cndmask_b32_e32 v48, v220, v48, vcc
	v_lshlrev_b32_e32 v93, 2, v48
	ds_read_b128 v[86:89], v125 offset:1024
	ds_read_b128 v[46:49], v120 offset:19456
	s_waitcnt lgkmcnt(0)
	v_mfma_f32_16x16x32_bf16 v[86:89], v[86:89], v[46:49], v[50:53]
	ds_read_b128 v[126:129], v125 offset:1088
	s_nop 1
	ds_read_b128 v[50:53], v120 offset:19520
	s_waitcnt lgkmcnt(0)
	v_mfma_f32_16x16x32_bf16 v[88:91], v[126:129], v[50:53], v[86:89]
	s_waitcnt vmcnt(3)
	s_nop 1
	v_lshlrev_b32_e32 v86, 16, v130
	v_mul_f32_e32 v61, 0xbfb8aa3b, v86
	v_exp_f32_e32 v61, v61
	v_and_b32_e32 v87, 0xffff0000, v130
	v_add_f32_e32 v61, 1.0, v61
	v_rcp_f32_e32 v126, v61
	v_mul_f32_e32 v61, 0xbfb8aa3b, v87
	v_exp_f32_e32 v61, v61
	s_nop 0
	v_add_f32_e32 v61, 1.0, v61
	v_rcp_f32_e32 v127, v61
	s_nop 0
	v_pk_mul_f32 v[86:87], v[126:127], v[86:87]
	s_nop 0
	v_pk_mul_f32 v[88:89], v[86:87], v[88:89]
	v_lshlrev_b32_e32 v86, 16, v131
	v_mul_f32_e32 v61, 0xbfb8aa3b, v86
	v_exp_f32_e32 v61, v61
	v_and_b32_e32 v87, 0xffff0000, v131
	v_add_f32_e32 v61, 1.0, v61
	v_rcp_f32_e32 v126, v61
	v_mul_f32_e32 v61, 0xbfb8aa3b, v87
	v_exp_f32_e32 v61, v61
	s_nop 0
	v_add_f32_e32 v61, 1.0, v61
	v_rcp_f32_e32 v127, v61
	s_nop 0
	v_pk_mul_f32 v[86:87], v[126:127], v[86:87]
	s_nop 0
	v_pk_mul_f32 v[90:91], v[86:87], v[90:91]
	v_pk_mul_f32 v[86:87], v[88:89], v[88:89]
	v_pk_mul_f32 v[126:127], v[90:91], v[90:91]
	v_add_f32_e32 v61, v86, v87
	v_add_f32_e32 v61, v126, v61
	v_add_f32_e32 v61, v127, v61
	ds_bpermute_b32 v86, v92, v61
	s_waitcnt lgkmcnt(0)
	v_add_f32_e32 v61, v61, v86
	ds_bpermute_b32 v86, v93, v61
	s_and_saveexec_b64 s[0:1], s[8:9]
	s_cbranch_execz .LBB0_314
	s_waitcnt lgkmcnt(0)
	v_add_f32_e32 v61, v61, v86
	global_atomic_add_f32 v[56:57], v61, off

.LBB0_353:
	s_or_b64 exec, exec, s[10:11]
	v_lshl_add_u64 v[8:9], v[22:23], 0, s[0:1]
	v_add_co_u32_e32 v40, vcc, 0xbe00000, v8
	s_mov_b32 s10, 0xbe01000
	s_nop 0
	v_addc_co_u32_e32 v41, vcc, 0, v9, vcc
	global_load_ushort v0, v[40:41], off
	v_mov_b32_e32 v150, 0x1000
	v_mov_b32_e32 v151, 0
	global_load_ushort v152, v[40:41], off offset:2048
	v_lshl_add_u64 v[144:145], v[40:41], 0, v[150:151]
	global_load_ushort v153, v[144:145], off
	global_load_ushort v154, v[144:145], off offset:2048
	v_lshl_add_u64 v[146:147], v[144:145], 0, v[150:151]
	global_load_ushort v155, v[146:147], off
	global_load_ushort v156, v[146:147], off offset:2048
	v_lshl_add_u64 v[148:149], v[146:147], 0, v[150:151]
	global_load_ushort v157, v[148:149], off
	global_load_ushort v158, v[148:149], off offset:2048
	s_waitcnt vmcnt(8)
	v_lshlrev_b32_e32 v2, 16, v2
	v_lshlrev_b32_e32 v3, 16, v3
	v_lshlrev_b32_e32 v7, 16, v7
	ds_read_b128 v[24:27], v52
	ds_read_b128 v[32:35], v52 offset:16
	v_add_co_u32_e32 v42, vcc, s10, v8
	s_mov_b32 s10, 0xbe02000
	s_nop 0
	v_addc_co_u32_e32 v43, vcc, 0, v9, vcc
	v_mov_b32_e32 v6, v3
	v_pk_fma_f32 v[2:3], v[10:11], v[2:3], v[18:19]
	s_add_u32 s0, s0, 0x4000
	v_pk_fma_f32 v[2:3], v[12:13], v[6:7], v[2:3]
	s_addc_u32 s1, s1, 0
	s_add_i32 s20, s20, 8
	s_add_i32 s13, s13, 8
	s_cmp_eq_u32 s0, 0x20000
	s_waitcnt vmcnt(0)
	v_lshlrev_b32_e32 v31, 16, v0
	s_waitcnt lgkmcnt(1)
	v_sub_f32_e32 v0, v51, v24
	v_mul_f32_e32 v0, 0x3fb8aa3b, v0
	v_exp_f32_e32 v4, v0
	v_sub_f32_e32 v0, v51, v25
	v_mul_f32_e32 v0, 0x3fb8aa3b, v0
	v_exp_f32_e32 v5, v0
	v_sub_f32_e32 v0, v51, v26
	v_mul_f32_e32 v0, 0x3fb8aa3b, v0
	v_exp_f32_e32 v28, v0
	v_sub_f32_e32 v0, v51, v27
	v_mul_f32_e32 v0, 0x3fb8aa3b, v0
	v_exp_f32_e32 v29, v0
	s_waitcnt lgkmcnt(0)
	v_sub_f32_e32 v0, v51, v32
	v_mul_f32_e32 v0, 0x3fb8aa3b, v0
	v_exp_f32_e32 v26, v0
	v_sub_f32_e32 v0, v51, v33
	v_mul_f32_e32 v0, 0x3fb8aa3b, v0
	v_exp_f32_e32 v27, v0
	v_sub_f32_e32 v0, v51, v34
	v_mul_f32_e32 v0, 0x3fb8aa3b, v0
	v_add_co_u32_e32 v34, vcc, s10, v8
	v_exp_f32_e32 v24, v0
	v_sub_f32_e32 v0, v51, v35
	v_addc_co_u32_e32 v35, vcc, 0, v9, vcc
	s_mov_b32 s10, 0xbe03000
	v_add_co_u32_e32 v8, vcc, s10, v8
	v_mul_f32_e32 v0, 0x3fb8aa3b, v0
	s_nop 0
	v_addc_co_u32_e32 v9, vcc, 0, v9, vcc
	v_exp_f32_e32 v25, v0
	v_mov_b32_e32 v0, v154
	v_mov_b32_e32 v30, v155
	v_mov_b32_e32 v44, v31
	s_waitcnt vmcnt(1)
	v_lshlrev_b32_e32 v32, 16, v0
	s_waitcnt vmcnt(0)
	v_lshlrev_b32_e32 v33, 16, v30
	v_mov_b32_e32 v0, v156
	v_mov_b32_e32 v30, v157
	s_nop 0
	v_mov_b32_e32 v8, v158
	v_mov_b32_e32 v38, v33
	s_waitcnt vmcnt(2)
	v_lshlrev_b32_e32 v34, 16, v0
	s_waitcnt vmcnt(1)
	v_lshlrev_b32_e32 v35, 16, v30
	s_waitcnt vmcnt(0)
	v_lshlrev_b32_e32 v37, 16, v8
	v_mov_b32_e32 v0, v152
	v_mov_b32_e32 v8, v153
	v_mov_b32_e32 v30, v7
	v_pk_fma_f32 v[2:3], v[14:15], v[30:31], v[2:3]
	v_pk_fma_f32 v[30:31], v[10:11], v[30:31], v[18:19]
	v_mov_b32_e32 v39, v34
	v_mov_b32_e32 v36, v35
	s_waitcnt vmcnt(1)
	v_lshlrev_b32_e32 v42, 16, v0
	v_mov_b32_e32 v45, v42
	v_pk_fma_f32 v[2:3], v[16:17], v[44:45], v[2:3]
	s_waitcnt vmcnt(0)
	v_lshlrev_b32_e32 v43, 16, v8
	v_mul_f32_e32 v0, 0xbfb8aa3b, v2
	v_exp_f32_e32 v0, v0
	v_pk_fma_f32 v[30:31], v[12:13], v[44:45], v[30:31]
	v_pk_mov_b32 v[54:55], v[42:43], v[32:33] op_sel:[1,0]
	v_pk_fma_f32 v[30:31], v[14:15], v[42:43], v[30:31]
	v_add_f32_e32 v0, 1.0, v0
	v_rcp_f32_e32 v40, v0
	v_mul_f32_e32 v0, 0xbfb8aa3b, v3
	v_exp_f32_e32 v0, v0
	v_pk_fma_f32 v[30:31], v[16:17], v[54:55], v[30:31]
	ds_read_b128 v[6:9], v52 offset:1024
	v_add_f32_e32 v0, 1.0, v0
	v_rcp_f32_e32 v41, v0
	v_mul_f32_e32 v0, 0xbfb8aa3b, v30
	v_exp_f32_e32 v0, v0
	v_pk_mul_f32 v[2:3], v[2:3], v[40:41]
	v_pk_fma_f32 v[40:41], v[10:11], v[42:43], v[18:19]
	v_add_f32_e32 v0, 1.0, v0
	v_rcp_f32_e32 v42, v0
	v_mul_f32_e32 v0, 0xbfb8aa3b, v31
	v_exp_f32_e32 v0, v0
	s_waitcnt lgkmcnt(0)
	v_pk_mul_f32 v[2:3], v[6:7], v[2:3]
	v_add_f32_e32 v0, 1.0, v0
	v_rcp_f32_e32 v43, v0
	v_pk_mul_f32 v[2:3], v[2:3], v[4:5]
	ds_read_b128 v[4:7], v52 offset:1040
	v_cvt_pk_bf16_f32 v2, v2, v3
	v_pk_mul_f32 v[30:31], v[30:31], v[42:43]
	v_add_u32_e32 v52, 32, v52
	v_pk_mul_f32 v[8:9], v[30:31], v[8:9]
	s_nop 0
	v_pk_mul_f32 v[8:9], v[8:9], v[28:29]
	v_pk_fma_f32 v[28:29], v[12:13], v[54:55], v[40:41]
	v_cvt_pk_bf16_f32 v3, v8, v9
	v_pk_mov_b32 v[8:9], v[32:33], v[34:35] op_sel:[1,0]
	v_pk_fma_f32 v[28:29], v[14:15], v[32:33], v[28:29]
	s_nop 0
	v_pk_fma_f32 v[8:9], v[16:17], v[8:9], v[28:29]
	s_nop 0
	v_mul_f32_e32 v0, 0xbfb8aa3b, v8
	v_exp_f32_e32 v0, v0
	s_nop 0
	v_add_f32_e32 v0, 1.0, v0
	v_rcp_f32_e32 v28, v0
	v_mul_f32_e32 v0, 0xbfb8aa3b, v9
	v_exp_f32_e32 v0, v0
	s_nop 0
	v_add_f32_e32 v0, 1.0, v0
	v_rcp_f32_e32 v29, v0
	s_nop 0
	v_pk_mul_f32 v[8:9], v[8:9], v[28:29]
	s_waitcnt lgkmcnt(0)
	v_pk_mul_f32 v[4:5], v[8:9], v[4:5]
	v_pk_fma_f32 v[8:9], v[10:11], v[32:33], v[18:19]
	v_pk_mul_f32 v[4:5], v[4:5], v[26:27]
	v_pk_fma_f32 v[8:9], v[12:13], v[38:39], v[8:9]
	v_cvt_pk_bf16_f32 v4, v4, v5
	v_pk_fma_f32 v[8:9], v[14:15], v[34:35], v[8:9]
	s_nop 0
	v_pk_fma_f32 v[8:9], v[16:17], v[36:37], v[8:9]
	s_nop 0
	v_mul_f32_e32 v0, 0xbfb8aa3b, v8
	v_exp_f32_e32 v0, v0
	s_nop 0
	v_add_f32_e32 v0, 1.0, v0
	v_rcp_f32_e32 v26, v0
	v_mul_f32_e32 v0, 0xbfb8aa3b, v9
	v_exp_f32_e32 v0, v0
	s_nop 0
	v_add_f32_e32 v0, 1.0, v0
	v_rcp_f32_e32 v27, v0
	s_nop 0
	v_pk_mul_f32 v[8:9], v[8:9], v[26:27]
	s_nop 0
	v_pk_mul_f32 v[6:7], v[8:9], v[6:7]
	s_nop 0
	v_pk_mul_f32 v[6:7], v[6:7], v[24:25]
	s_nop 0
	v_cvt_pk_bf16_f32 v5, v6, v7
	ds_write_b128 v53, v[2:5]
	v_add_u32_e32 v53, 16, v53
	s_cbranch_scc1 .LBB0_360
.LBB0_354:
	v_add_u32_e32 v0, s13, v50
	v_add_u32_e32 v2, 61, v0
	v_cmp_lt_i32_e32 vcc, s12, v2
	v_mov_b32_e32 v3, 0
	v_mov_b32_e32 v2, 0
	s_and_saveexec_b64 s[10:11], vcc
	s_cbranch_execz .LBB0_356
	v_add3_u32 v4, v50, s20, -3
	v_ashrrev_i32_e32 v5, 31, v4
	v_lshlrev_b64 v[4:5], 11, v[4:5]
	v_lshl_add_u64 v[4:5], v[20:21], 0, v[4:5]
	global_load_ushort v2, v[4:5], off
.LBB0_356:
	s_or_b64 exec, exec, s[10:11]
	v_add_u32_e32 v4, 62, v0
	v_cmp_lt_i32_e32 vcc, s12, v4
	s_and_saveexec_b64 s[10:11], vcc
	s_cbranch_execz .LBB0_358
	v_add3_u32 v4, v50, s20, -2
	v_ashrrev_i32_e32 v5, 31, v4
	v_lshlrev_b64 v[4:5], 11, v[4:5]
	v_lshl_add_u64 v[4:5], v[20:21], 0, v[4:5]
	global_load_ushort v3, v[4:5], off
.LBB0_358:
	s_or_b64 exec, exec, s[10:11]
	v_add_u32_e32 v0, 63, v0
	v_cmp_lt_i32_e32 vcc, s12, v0
	v_mov_b32_e32 v7, 0
	s_and_saveexec_b64 s[10:11], vcc
	s_cbranch_execz .LBB0_353
	v_add3_u32 v4, v50, s20, -1
	v_ashrrev_i32_e32 v5, 31, v4
	v_lshlrev_b64 v[4:5], 11, v[4:5]
	v_lshl_add_u64 v[4:5], v[20:21], 0, v[4:5]
	global_load_ushort v7, v[4:5], off
	s_branch .LBB0_353
.LBB0_360:
	s_lshl_b32 s0, s19, 5
	s_add_i32 s0, s8, s0
	s_ashr_i32 s1, s0, 31
	s_lshl_b64 s[10:11], s[0:1], 15
	s_add_u32 s10, s88, s10
	v_or_b32_e32 v2, s18, v48
	s_addc_u32 s11, s89, s11
	v_ashrrev_i32_e32 v3, 31, v2
	s_lshl_b32 s8, s8, 4
	v_lshlrev_b64 v[2:3], 11, v[2:3]
	s_and_b32 s12, s8, 0xffffff80
	v_lshl_add_u64 v[2:3], s[60:61], 0, v[2:3]
	s_ashr_i32 s13, s12, 31
	v_lshl_add_u64 v[2:3], s[12:13], 1, v[2:3]
	v_readlane_b32 s18, v253, 57
	s_movk_i32 s8, 0x210
	s_nop 1
	v_lshl_add_u32 v0, v48, 1, s18
	v_ashrrev_i32_e32 v4, 5, v49
	v_and_b32_e32 v4, -8, v4
	v_ashrrev_i32_e32 v5, 31, v4
	v_lshl_add_u64 v[6:7], v[4:5], 1, v[2:3]
	v_mad_u64_u32 v[196:197], s[12:13], v4, s8, v[0:1]
	global_load_dwordx4 v[164:167], v[6:7], off
	v_add_u32_e32 v4, 0x200, v49
	v_ashrrev_i32_e32 v4, 5, v4
	v_and_b32_e32 v4, -8, v4
	v_ashrrev_i32_e32 v5, 31, v4
	v_lshl_add_u64 v[6:7], v[4:5], 1, v[2:3]
	v_mad_u64_u32 v[198:199], s[12:13], v4, s8, v[0:1]
	global_load_dwordx4 v[168:171], v[6:7], off
	v_add_u32_e32 v4, 0x400, v49
	v_ashrrev_i32_e32 v4, 5, v4
	v_and_b32_e32 v4, -8, v4
	v_ashrrev_i32_e32 v5, 31, v4
	v_lshl_add_u64 v[6:7], v[4:5], 1, v[2:3]
	v_mad_u64_u32 v[200:201], s[12:13], v4, s8, v[0:1]
	global_load_dwordx4 v[172:175], v[6:7], off
	v_add_u32_e32 v4, 0x600, v49
	v_ashrrev_i32_e32 v4, 5, v4
	v_and_b32_e32 v4, -8, v4
	v_ashrrev_i32_e32 v5, 31, v4
	v_lshl_add_u64 v[6:7], v[4:5], 1, v[2:3]
	v_mad_u64_u32 v[202:203], s[12:13], v4, s8, v[0:1]
	global_load_dwordx4 v[176:179], v[6:7], off
	v_add_u32_e32 v4, 0x800, v49
	v_ashrrev_i32_e32 v4, 5, v4
	v_and_b32_e32 v4, -8, v4
	v_ashrrev_i32_e32 v5, 31, v4
	v_lshl_add_u64 v[6:7], v[4:5], 1, v[2:3]
	v_mad_u64_u32 v[204:205], s[12:13], v4, s8, v[0:1]
	global_load_dwordx4 v[180:183], v[6:7], off
	v_add_u32_e32 v4, 0xa00, v49
	v_ashrrev_i32_e32 v4, 5, v4
	v_and_b32_e32 v4, -8, v4
	v_ashrrev_i32_e32 v5, 31, v4
	v_lshl_add_u64 v[6:7], v[4:5], 1, v[2:3]
	v_mad_u64_u32 v[206:207], s[12:13], v4, s8, v[0:1]
	global_load_dwordx4 v[184:187], v[6:7], off
	v_add_u32_e32 v4, 0xc00, v49
	v_ashrrev_i32_e32 v4, 5, v4
	v_and_b32_e32 v4, -8, v4
	v_ashrrev_i32_e32 v5, 31, v4
	v_lshl_add_u64 v[6:7], v[4:5], 1, v[2:3]
	v_mad_u64_u32 v[208:209], s[12:13], v4, s8, v[0:1]
	global_load_dwordx4 v[188:191], v[6:7], off
	v_add_u32_e32 v4, 0xe00, v49
	v_ashrrev_i32_e32 v4, 5, v4
	v_and_b32_e32 v4, -8, v4
	v_ashrrev_i32_e32 v5, 31, v4
	v_lshl_add_u64 v[6:7], v[4:5], 1, v[2:3]
	v_mad_u64_u32 v[210:211], s[12:13], v4, s8, v[0:1]
	global_load_dwordx4 v[192:195], v[6:7], off
	v_lshlrev_b32_e32 v46, 4, v46
	v_lshl_or_b32 v142, s17, 13, v46
	v_cmp_eq_u32_e32 vcc, 0, v48
	s_waitcnt vmcnt(7)
	ds_write_b16 v196, v164
	ds_write_b16_d16_hi v196, v164 offset:528
	ds_write_b16 v196, v165 offset:1056
	ds_write_b16_d16_hi v196, v165 offset:1584
	ds_write_b16 v196, v166 offset:2112
	ds_write_b16_d16_hi v196, v166 offset:2640
	ds_write_b16 v196, v167 offset:3168
	ds_write_b16_d16_hi v196, v167 offset:3696
	s_waitcnt vmcnt(6)
	ds_write_b16 v198, v168
	ds_write_b16_d16_hi v198, v168 offset:528
	ds_write_b16 v198, v169 offset:1056
	ds_write_b16_d16_hi v198, v169 offset:1584
	ds_write_b16 v198, v170 offset:2112
	ds_write_b16_d16_hi v198, v170 offset:2640
	ds_write_b16 v198, v171 offset:3168
	ds_write_b16_d16_hi v198, v171 offset:3696
	s_waitcnt vmcnt(5)
	ds_write_b16 v200, v172
	ds_write_b16_d16_hi v200, v172 offset:528
	ds_write_b16 v200, v173 offset:1056
	ds_write_b16_d16_hi v200, v173 offset:1584
	ds_write_b16 v200, v174 offset:2112
	ds_write_b16_d16_hi v200, v174 offset:2640
	ds_write_b16 v200, v175 offset:3168
	ds_write_b16_d16_hi v200, v175 offset:3696
	s_waitcnt vmcnt(4)
	ds_write_b16 v202, v176
	ds_write_b16_d16_hi v202, v176 offset:528
	ds_write_b16 v202, v177 offset:1056
	ds_write_b16_d16_hi v202, v177 offset:1584
	ds_write_b16 v202, v178 offset:2112
	ds_write_b16_d16_hi v202, v178 offset:2640
	ds_write_b16 v202, v179 offset:3168
	ds_write_b16_d16_hi v202, v179 offset:3696
	s_waitcnt vmcnt(3)
	ds_write_b16 v204, v180
	ds_write_b16_d16_hi v204, v180 offset:528
	ds_write_b16 v204, v181 offset:1056
	ds_write_b16_d16_hi v204, v181 offset:1584
	ds_write_b16 v204, v182 offset:2112
	ds_write_b16_d16_hi v204, v182 offset:2640
	ds_write_b16 v204, v183 offset:3168
	ds_write_b16_d16_hi v204, v183 offset:3696
	s_waitcnt vmcnt(2)
	ds_write_b16 v206, v184
	ds_write_b16_d16_hi v206, v184 offset:528
	ds_write_b16 v206, v185 offset:1056
	ds_write_b16_d16_hi v206, v185 offset:1584
	ds_write_b16 v206, v186 offset:2112
	ds_write_b16_d16_hi v206, v186 offset:2640
	ds_write_b16 v206, v187 offset:3168
	ds_write_b16_d16_hi v206, v187 offset:3696
	s_waitcnt vmcnt(1)
	ds_write_b16 v208, v188
	ds_write_b16_d16_hi v208, v188 offset:528
	ds_write_b16 v208, v189 offset:1056
	ds_write_b16_d16_hi v208, v189 offset:1584
	ds_write_b16 v208, v190 offset:2112
	ds_write_b16_d16_hi v208, v190 offset:2640
	ds_write_b16 v208, v191 offset:3168
	ds_write_b16_d16_hi v208, v191 offset:3696
	s_waitcnt vmcnt(0)
	ds_write_b16 v210, v192
	ds_write_b16_d16_hi v210, v192 offset:528
	ds_write_b16 v210, v193 offset:1056
	ds_write_b16_d16_hi v210, v193 offset:1584
	ds_write_b16 v210, v194 offset:2112
	ds_write_b16_d16_hi v210, v194 offset:2640
	ds_write_b16 v210, v195 offset:3168
	ds_write_b16_d16_hi v210, v195 offset:3696
	v_and_b32_e32 v0, 15, v49
	v_mul_u32_u24_e32 v0, 0x210, v0
	s_lshl_b32 s8, s17, 1
	s_or_b32 s8, s8, 1
	v_and_b32_e32 v2, 48, v49
	v_add3_u32 v49, s18, v0, v2
	v_add3_u32 v0, s9, v0, v2
	s_mul_i32 s9, s17, 0x4200
	v_add_u32_e32 v66, s9, v49
	s_waitcnt lgkmcnt(0)
	s_barrier
	ds_read_b128 v[18:21], v66
	ds_read_b128 v[2:5], v0 offset:2304
	ds_read_b128 v[22:25], v66 offset:64
	ds_read_b128 v[6:9], v0 offset:2368
	s_waitcnt lgkmcnt(2)
	v_mfma_f32_16x16x32_bf16 v[10:13], v[18:21], v[2:5], 0
	s_mul_i32 s9, s8, 0x2100
	s_waitcnt lgkmcnt(0)
	v_mfma_f32_16x16x32_bf16 v[14:17], v[22:25], v[6:9], v[10:13]
	ds_read_b128 v[26:29], v66 offset:128
	s_nop 3
	ds_read_b128 v[10:13], v0 offset:2432
	s_waitcnt lgkmcnt(0)
	v_mfma_f32_16x16x32_bf16 v[30:33], v[26:29], v[10:13], v[14:17]
	ds_read_b128 v[34:37], v66 offset:192
	s_nop 1
	ds_read_b128 v[14:17], v0 offset:2496
	ds_read_b128 v[38:41], v66 offset:256
	ds_read_b128 v[42:45], v0 offset:2560
	ds_read_b128 v[50:53], v66 offset:320
	ds_read_b128 v[54:57], v0 offset:2624
	s_waitcnt lgkmcnt(4)
	v_mfma_f32_16x16x32_bf16 v[30:33], v[34:37], v[14:17], v[30:33]
	ds_read_b128 v[58:61], v66 offset:384
	ds_read_b128 v[62:65], v0 offset:2688
	ds_read_b128 v[66:69], v66 offset:448
	ds_read_b128 v[70:73], v0 offset:2752
	ds_read_b128 v[78:81], v0 offset:10816
	s_waitcnt lgkmcnt(7)
	v_mfma_f32_16x16x32_bf16 v[30:33], v[38:41], v[42:45], v[30:33]
	ds_read_b128 v[82:85], v0 offset:10880
	ds_read_b128 v[86:89], v0 offset:10944
	ds_read_b128 v[90:93], v0 offset:11008
	ds_read_b128 v[94:97], v0 offset:11072
	s_waitcnt lgkmcnt(9)
	v_mfma_f32_16x16x32_bf16 v[30:33], v[50:53], v[54:57], v[30:33]
	ds_read_b128 v[98:101], v0 offset:11136
	ds_read_b128 v[102:105], v0 offset:11200
	ds_read_b128 v[114:117], v0 offset:19328
	ds_read_b128 v[118:121], v0 offset:19392
	s_waitcnt lgkmcnt(11)
	v_mfma_f32_16x16x32_bf16 v[30:33], v[58:61], v[62:65], v[30:33]
	ds_read_b128 v[110:113], v0 offset:19264
	ds_read_b128 v[122:125], v0 offset:19456
	ds_read_b128 v[126:129], v0 offset:19520
	s_waitcnt lgkmcnt(12)
	v_mfma_f32_16x16x32_bf16 v[30:33], v[66:69], v[70:73], v[30:33]
	ds_read_b128 v[130:133], v0 offset:19584
	ds_read_b128 v[134:137], v0 offset:19648
	ds_read_b128 v[138:141], v0 offset:27712
	s_nop 4
	global_store_dwordx4 v142, v[30:33], s[10:11]
	ds_read_b128 v[30:33], v0 offset:10752
	s_waitcnt lgkmcnt(0)
	v_mfma_f32_16x16x32_bf16 v[74:77], v[18:21], v[30:33], 0
	v_mfma_f32_16x16x32_bf16 v[74:77], v[22:25], v[78:81], v[74:77]
	v_mfma_f32_16x16x32_bf16 v[74:77], v[26:29], v[82:85], v[74:77]
	v_mfma_f32_16x16x32_bf16 v[74:77], v[34:37], v[86:89], v[74:77]
	v_mfma_f32_16x16x32_bf16 v[74:77], v[38:41], v[90:93], v[74:77]
	v_mfma_f32_16x16x32_bf16 v[74:77], v[50:53], v[94:97], v[74:77]
	v_mfma_f32_16x16x32_bf16 v[74:77], v[58:61], v[98:101], v[74:77]
	v_mfma_f32_16x16x32_bf16 v[74:77], v[66:69], v[102:105], v[74:77]
	s_nop 7
	global_store_dwordx4 v142, v[74:77], s[10:11] offset:1024
	ds_read_b128 v[74:77], v0 offset:19200
	s_waitcnt lgkmcnt(0)
	v_mfma_f32_16x16x32_bf16 v[106:109], v[18:21], v[74:77], 0
	v_mfma_f32_16x16x32_bf16 v[106:109], v[22:25], v[110:113], v[106:109]
	v_mfma_f32_16x16x32_bf16 v[106:109], v[26:29], v[114:117], v[106:109]
	v_mfma_f32_16x16x32_bf16 v[106:109], v[34:37], v[118:121], v[106:109]
	v_mfma_f32_16x16x32_bf16 v[106:109], v[38:41], v[122:125], v[106:109]
	v_mfma_f32_16x16x32_bf16 v[106:109], v[50:53], v[126:129], v[106:109]
	v_mfma_f32_16x16x32_bf16 v[106:109], v[58:61], v[130:133], v[106:109]
	v_mfma_f32_16x16x32_bf16 v[106:109], v[66:69], v[134:137], v[106:109]
	s_nop 7
	global_store_dwordx4 v142, v[106:109], s[10:11] offset:2048
	ds_read_b128 v[106:109], v0 offset:27648
	s_waitcnt lgkmcnt(0)
	v_mfma_f32_16x16x32_bf16 v[18:21], v[18:21], v[106:109], 0
	v_mfma_f32_16x16x32_bf16 v[18:21], v[22:25], v[138:141], v[18:21]
	ds_read_b128 v[22:25], v0 offset:27776
	s_waitcnt lgkmcnt(0)
	v_mfma_f32_16x16x32_bf16 v[18:21], v[26:29], v[22:25], v[18:21]
	ds_read_b128 v[26:29], v0 offset:27840
	s_waitcnt lgkmcnt(0)
	v_mfma_f32_16x16x32_bf16 v[18:21], v[34:37], v[26:29], v[18:21]
	ds_read_b128 v[34:37], v0 offset:27904
	s_waitcnt lgkmcnt(0)
	v_mfma_f32_16x16x32_bf16 v[18:21], v[38:41], v[34:37], v[18:21]
	ds_read_b128 v[38:41], v0 offset:27968
	s_waitcnt lgkmcnt(0)
	v_mfma_f32_16x16x32_bf16 v[18:21], v[50:53], v[38:41], v[18:21]
	ds_read_b128 v[50:53], v0 offset:28032
	s_waitcnt lgkmcnt(0)
	v_mfma_f32_16x16x32_bf16 v[18:21], v[58:61], v[50:53], v[18:21]
	ds_read_b128 v[58:61], v0 offset:28096
	v_add_u32_e32 v0, s9, v49
	s_waitcnt lgkmcnt(0)
	v_mfma_f32_16x16x32_bf16 v[18:21], v[66:69], v[58:61], v[18:21]
	ds_read_b128 v[66:69], v0 offset:64
	s_nop 6
	global_store_dwordx4 v142, v[18:21], s[10:11] offset:3072
	ds_read_b128 v[18:21], v0
	s_waitcnt lgkmcnt(0)
	v_mfma_f32_16x16x32_bf16 v[2:5], v[18:21], v[2:5], 0
	v_mfma_f32_16x16x32_bf16 v[2:5], v[66:69], v[6:9], v[2:5]
	ds_read_b128 v[6:9], v0 offset:128
	s_waitcnt lgkmcnt(0)
	v_mfma_f32_16x16x32_bf16 v[2:5], v[6:9], v[10:13], v[2:5]
	ds_read_b128 v[10:13], v0 offset:192
	s_waitcnt lgkmcnt(0)
	v_mfma_f32_16x16x32_bf16 v[2:5], v[10:13], v[14:17], v[2:5]
	ds_read_b128 v[14:17], v0 offset:256
	s_waitcnt lgkmcnt(0)
	v_mfma_f32_16x16x32_bf16 v[2:5], v[14:17], v[42:45], v[2:5]
	ds_read_b128 v[42:45], v0 offset:320
	s_waitcnt lgkmcnt(0)
	v_mfma_f32_16x16x32_bf16 v[2:5], v[42:45], v[54:57], v[2:5]
	ds_read_b128 v[54:57], v0 offset:384
	s_waitcnt lgkmcnt(0)
	v_mfma_f32_16x16x32_bf16 v[2:5], v[54:57], v[62:65], v[2:5]
	ds_read_b128 v[62:65], v0 offset:448
	v_lshl_or_b32 v0, s8, 12, v46
	s_waitcnt lgkmcnt(0)
	v_mfma_f32_16x16x32_bf16 v[2:5], v[62:65], v[70:73], v[2:5]
	s_nop 7
	global_store_dwordx4 v0, v[2:5], s[10:11]
	s_nop 1
	v_mfma_f32_16x16x32_bf16 v[2:5], v[18:21], v[30:33], 0
	v_mfma_f32_16x16x32_bf16 v[2:5], v[66:69], v[78:81], v[2:5]
	v_mfma_f32_16x16x32_bf16 v[2:5], v[6:9], v[82:85], v[2:5]
	v_mfma_f32_16x16x32_bf16 v[2:5], v[10:13], v[86:89], v[2:5]
	v_mfma_f32_16x16x32_bf16 v[2:5], v[14:17], v[90:93], v[2:5]
	v_mfma_f32_16x16x32_bf16 v[2:5], v[42:45], v[94:97], v[2:5]
	v_mfma_f32_16x16x32_bf16 v[2:5], v[54:57], v[98:101], v[2:5]
	v_mfma_f32_16x16x32_bf16 v[2:5], v[62:65], v[102:105], v[2:5]
	s_nop 7
	global_store_dwordx4 v0, v[2:5], s[10:11] offset:1024
	s_nop 1
	v_mfma_f32_16x16x32_bf16 v[2:5], v[18:21], v[74:77], 0
	v_mfma_f32_16x16x32_bf16 v[2:5], v[66:69], v[110:113], v[2:5]
	v_mfma_f32_16x16x32_bf16 v[2:5], v[6:9], v[114:117], v[2:5]
	v_mfma_f32_16x16x32_bf16 v[2:5], v[10:13], v[118:121], v[2:5]
	v_mfma_f32_16x16x32_bf16 v[2:5], v[14:17], v[122:125], v[2:5]
	v_mfma_f32_16x16x32_bf16 v[2:5], v[42:45], v[126:129], v[2:5]
	v_mfma_f32_16x16x32_bf16 v[2:5], v[54:57], v[130:133], v[2:5]
	v_mfma_f32_16x16x32_bf16 v[2:5], v[62:65], v[134:137], v[2:5]
	s_nop 7
	global_store_dwordx4 v0, v[2:5], s[10:11] offset:2048
	s_nop 1
	v_mfma_f32_16x16x32_bf16 v[2:5], v[18:21], v[106:109], 0
	v_mfma_f32_16x16x32_bf16 v[2:5], v[66:69], v[138:141], v[2:5]
	v_mfma_f32_16x16x32_bf16 v[2:5], v[6:9], v[22:25], v[2:5]
	v_mfma_f32_16x16x32_bf16 v[2:5], v[10:13], v[26:29], v[2:5]
	v_mfma_f32_16x16x32_bf16 v[2:5], v[14:17], v[34:37], v[2:5]
	v_mfma_f32_16x16x32_bf16 v[2:5], v[42:45], v[38:41], v[2:5]
	v_mfma_f32_16x16x32_bf16 v[2:5], v[54:57], v[50:53], v[2:5]
	v_mfma_f32_16x16x32_bf16 v[2:5], v[62:65], v[58:61], v[2:5]
	s_nop 7
	global_store_dwordx4 v0, v[2:5], s[10:11] offset:3072
	s_and_saveexec_b64 s[8:9], vcc
	s_cbranch_execz .LBB0_339
	v_mul_f32_e32 v0, 0x3fb8aa3b, v47
	v_exp_f32_e32 v0, v0
	s_lshl_b64 s[0:1], s[0:1], 2
	s_add_u32 s0, s24, s0
	s_addc_u32 s1, s25, s1
	global_store_dword v1, v0, s[0:1]
	s_branch .LBB0_339
